# GQA pass prologue: tile 0/1 staging loads hoisted behind the Q loads (tests whether overlapping the two global latencies pays)
# baseline (speedup 1.0000x reference)
; __device__ __forceinline__ float bf2f(unsigned short b) { return __uint_as_float((unsigned)b << 16); }
; __device__ __forceinline__ float sum_x32(float v) { auto rr = __builtin_amdgcn_permlane32_swap(__float_as_uint(v), __float_as_uint(v), false, false); return __uint_as_float(rr[0]) + __uint_as_float(rr[1]); }
; __device__ __forceinline__ void attn_pass_A2(const int tid, unsigned char* smem, const bf16_t* Q0w, int qpitch, const bf16_t* Kb, int kpitch, const bf16_t* Vb, int vpitch,
;                                              int b, int ntiles, float kmax, f32x16 (&o)[2][2], float (&linv)[2]) {
;     ...
;     unsigned char* qs = smem + 2 * BUF + ((tid >> 6) * 64 + r32) * KP + hi * 16;
; #pragma unroll
;     for (int qb = 0; qb < 2; ++qb) {
;         const bf16_t* qp = Q0w + (size_t)(32 * qb + r32) * qpitch + 8 * hi; float ssq = 0.f;
; #pragma unroll
;         for (int ds = 0; ds < 4; ++ds) { const bf16x8 qv = *(const bf16x8*)(qp + 16 * ds); *(bf16x8*)(qs + qb * 32 * KP + ds * 32) = qv;
; #pragma unroll
;             for (int j = 0; j < 8; ++j) { const float f = bf2f((unsigned short)qv[j]); ssq += f * f; } }
;         nshift[qb] = -sqrtf(sum_x32(ssq)) * kmax;
; #pragma unroll
;         for (int d0 = 0; d0 < 2; ++d0)
; #pragma unroll
;             for (int r = 0; r < 16; ++r) o[qb][d0][r] = 0.f;
;     }
;     const int krow = tid >> 3, kch = tid & 7;
;     u32x4 kreg, vreg;
;     auto gload = [&](int kt) {
;         const size_t rb = kt < 4 ? (size_t)(NLAT + 256 * b + 64 * kt) : (size_t)(SEQ * b + 64 * (kt - 4));
;         kreg = *(const u32x4*)(Kb + (rb + krow) * kpitch + 8 * kch); vreg = *(const u32x4*)(Vb + (rb + krow) * vpitch + 8 * kch);
;     };
;     auto lwrite = [&](int buf) { unsigned char* Ks = smem + buf * BUF; *(u32x4*)(Ks + krow * KP + 16 * kch) = kreg; *(u32x4*)(Ks + KBYTES + krow * VP + 16 * kch) = vreg; };
;     gload(0); lwrite(0); __syncthreads();
.LBB0_417:
	s_and_b64 vcc, exec, s[0:1]
	s_cbranch_vccz .LBB0_394
	s_and_b32 s0, s27, 0xffffffc0
	s_add_i32 s1, s0, 0xffffff00
	s_cmp_lt_i32 s0, s11
	s_cselect_b32 s0, s0, s1
	s_ashr_i32 s1, s0, 31
	s_add_u32 s0, s8, s0
	s_addc_u32 s1, s9, s1
	s_lshl_b64 s[0:1], s[0:1], 11
	v_readlane_b32 s2, v253, 22
	v_readlane_b32 s3, v253, 23
	s_add_u32 s2, s2, s0
	s_addc_u32 s3, s3, s1
	s_lshl_b32 s0, s26, 6
	s_ashr_i32 s1, s0, 31
	s_lshl_b64 s[12:13], s[0:1], 1
	s_add_u32 s0, s2, s12
	s_addc_u32 s1, s3, s13
	v_mov_b32_e32 v139, v193
	v_lshl_add_u64 v[0:1], s[0:1], 0, v[138:139]
	v_lshlrev_b32_e32 v192, 11, v218
	v_lshl_add_u64 v[0:1], v[0:1], 0, v[192:193]
	global_load_dwordx4 v[20:23], v[0:1], off
	global_load_dwordx4 v[24:27], v[0:1], off offset:32
	global_load_dwordx4 v[28:31], v[0:1], off offset:64
	global_load_dwordx4 v[32:35], v[0:1], off offset:96
	s_mov_b32 s0, 0x10000
	v_add_co_u32_e32 v10, vcc, s0, v0
	s_movk_i32 s0, 0x90
	s_nop 0
	v_addc_co_u32_e32 v11, vcc, 0, v1, vcc
	global_load_dwordx4 v[16:19], v[10:11], off
	v_and_b32_e32 v1, 0xfffffdf, v197
	v_mul_lo_u32 v1, v1, s0
	v_add_u32_e32 v1, 0, v1
	v_add_u32_e32 v139, v1, v138
	global_load_dwordx4 v[2:5], v[10:11], off offset:32
	global_load_dwordx4 v[6:9], v[10:11], off offset:64
	s_nop 0
	global_load_dwordx4 v[10:13], v[10:11], off offset:96
	s_lshl_b32 s0, s26, 4
	s_andn2_b32 s0, s0, 63
	s_ashr_i32 s1, s0, 31
	s_lshl_b64 s[0:1], s[0:1], 1
	v_readlane_b32 s2, v251, 33
	s_add_u32 s14, s2, s0
	v_readlane_b32 s2, v251, 34
	s_addc_u32 s15, s2, s1
	v_readlane_b32 s2, v251, 35
	s_add_u32 s16, s2, s0
	s_mov_b32 s2, 0xf800000
	v_readlane_b32 s0, v251, 36
	s_addc_u32 s17, s0, s1
	v_and_b32_e32 v192, 0x70, v217
	v_mov_b32_e32 v0, 0
	s_mov_b32 s3, 0
	v_lshl_add_u64 v[140:141], s[14:15], 0, v[192:193]
	v_lshl_add_u64 v[142:143], s[16:17], 0, v[192:193]
	s_mov_b64 s[66:67], s[14:15]
	s_mov_b64 s[68:69], s[16:17]
	s_lshl_b32 s96, s10, 8
	s_add_i32 s65, s96, 0x8000
	s_lshl_b32 s96, s10, 13
	s_add_i32 s32, s96, 0xffffff00
	v_lshl_add_u32 v236, v136, 8, v192
	s_lshl_b32 s96, s65, 8
	s_add_u32 s60, s66, s96
	s_addc_u32 s61, s67, 0
	s_add_u32 s62, s68, s96
	s_addc_u32 s63, s69, 0
	global_load_dwordx4 v[128:131], v236, s[60:61]
	global_load_dwordx4 v[132:135], v236, s[62:63]
	s_add_i32 s96, s65, 64
	s_lshl_b32 s96, s96, 8
	s_add_u32 s60, s66, s96
	s_addc_u32 s61, s67, 0
	s_add_u32 s62, s68, s96
	s_addc_u32 s63, s69, 0
	global_load_dwordx4 v[222:225], v236, s[60:61]
	global_load_dwordx4 v[230:233], v236, s[62:63]
	v_mul_u32_u24_e32 v173, 0xc0, v215
	v_lshlrev_b32_e32 v174, 1, v216
	v_mov_b32_e32 v52, v0
	v_mov_b32_e32 v53, v0
	v_mov_b32_e32 v54, v0
	v_mov_b32_e32 v55, v0
	v_mov_b32_e32 v56, v0
	v_mov_b32_e32 v57, v0
	v_mov_b32_e32 v58, v0
	v_mov_b32_e32 v59, v0
	v_mov_b32_e32 v60, v0
	v_mov_b32_e32 v61, v0
	v_mov_b32_e32 v62, v0
	v_mov_b32_e32 v63, v0
	v_mov_b32_e32 v64, v0
	v_mov_b32_e32 v65, v0
	v_mov_b32_e32 v66, v0
	v_mov_b32_e32 v67, v0
	v_mov_b32_e32 v68, v0
	v_mov_b32_e32 v69, v0
	v_mov_b32_e32 v70, v0
	v_mov_b32_e32 v71, v0
	v_mov_b32_e32 v72, v0
	v_mov_b32_e32 v73, v0
	v_mov_b32_e32 v74, v0
	v_mov_b32_e32 v75, v0
	v_mov_b32_e32 v76, v0
	v_mov_b32_e32 v77, v0
	v_mov_b32_e32 v78, v0
	v_mov_b32_e32 v79, v0
	v_mov_b32_e32 v144, v0
	v_mov_b32_e32 v145, v0
	s_waitcnt vmcnt(7)
	v_and_b32_e32 v36, 0xffff0000, v20
	v_lshlrev_b32_e32 v1, 16, v20
	v_lshlrev_b32_e32 v37, 16, v21
	s_waitcnt vmcnt(4)
	ds_write_b128 v139, v[32:35] offset:43104
	v_and_b32_e32 v15, 0xffff0000, v34
	v_lshlrev_b32_e32 v14, 16, v34
	v_mul_f32_e32 v34, v36, v36
	v_fmac_f32_e32 v34, v1, v1
	v_and_b32_e32 v38, 0xffff0000, v21
	v_fmac_f32_e32 v34, v37, v37
	v_lshlrev_b32_e32 v39, 16, v22
	v_fmac_f32_e32 v34, v38, v38
	ds_write_b128 v139, v[20:23] offset:43008
	v_and_b32_e32 v22, 0xffff0000, v22
	v_fmac_f32_e32 v34, v39, v39
	v_lshlrev_b32_e32 v40, 16, v23
	v_fmac_f32_e32 v34, v22, v22
	v_and_b32_e32 v23, 0xffff0000, v23
	v_fmac_f32_e32 v34, v40, v40
	v_lshlrev_b32_e32 v41, 16, v24
	v_fmac_f32_e32 v34, v23, v23
	ds_write_b128 v139, v[24:27] offset:43040
	v_and_b32_e32 v24, 0xffff0000, v24
	v_fmac_f32_e32 v34, v41, v41
	v_lshlrev_b32_e32 v42, 16, v25
	v_fmac_f32_e32 v34, v24, v24
	v_and_b32_e32 v25, 0xffff0000, v25
	v_fmac_f32_e32 v34, v42, v42
	v_lshlrev_b32_e32 v43, 16, v26
	v_fmac_f32_e32 v34, v25, v25
	v_and_b32_e32 v26, 0xffff0000, v26
	v_fmac_f32_e32 v34, v43, v43
	v_lshlrev_b32_e32 v44, 16, v27
	v_fmac_f32_e32 v34, v26, v26
	v_and_b32_e32 v27, 0xffff0000, v27
	v_fmac_f32_e32 v34, v44, v44
	v_lshlrev_b32_e32 v45, 16, v28
	v_fmac_f32_e32 v34, v27, v27
	ds_write_b128 v139, v[28:31] offset:43072
	v_and_b32_e32 v28, 0xffff0000, v28
	v_fmac_f32_e32 v34, v45, v45
	v_lshlrev_b32_e32 v46, 16, v29
	v_fmac_f32_e32 v34, v28, v28
	v_and_b32_e32 v29, 0xffff0000, v29
	v_fmac_f32_e32 v34, v46, v46
	v_lshlrev_b32_e32 v47, 16, v30
	v_fmac_f32_e32 v34, v29, v29
	v_and_b32_e32 v30, 0xffff0000, v30
	v_fmac_f32_e32 v34, v47, v47
	v_lshlrev_b32_e32 v48, 16, v31
	v_fmac_f32_e32 v34, v30, v30
	v_and_b32_e32 v31, 0xffff0000, v31
	v_fmac_f32_e32 v34, v48, v48
	v_lshlrev_b32_e32 v49, 16, v32
	v_fmac_f32_e32 v34, v31, v31
	v_and_b32_e32 v32, 0xffff0000, v32
	v_fmac_f32_e32 v34, v49, v49
	v_lshlrev_b32_e32 v50, 16, v33
	v_fmac_f32_e32 v34, v32, v32
	v_and_b32_e32 v33, 0xffff0000, v33
	v_fmac_f32_e32 v34, v50, v50
	v_pk_mul_f32 v[14:15], v[14:15], v[14:15]
	v_fmac_f32_e32 v34, v33, v33
	v_and_b32_e32 v21, 0xffff0000, v35
	v_lshlrev_b32_e32 v20, 16, v35
	v_add_f32_e32 v14, v14, v34
	v_pk_mul_f32 v[20:21], v[20:21], v[20:21]
	v_add_f32_e32 v14, v15, v14
	v_add_f32_e32 v14, v20, v14
	v_add_f32_e32 v14, v21, v14
	v_mov_b32_e32 v15, v14
	s_nop 1
	v_permlane32_swap_b32_e32 v14, v15
	v_add_f32_e32 v14, v14, v15
	v_mul_f32_e32 v15, 0x4f800000, v14
	v_cmp_gt_f32_e32 vcc, s2, v14
	s_waitcnt vmcnt(3)
; __device__ __forceinline__ float bf2f(unsigned short b) { return __uint_as_float((unsigned)b << 16); }
; __device__ __forceinline__ float sum_x32(float v) { auto rr = __builtin_amdgcn_permlane32_swap(__float_as_uint(v), __float_as_uint(v), false, false); return __uint_as_float(rr[0]) + __uint_as_float(rr[1]); }
; __device__ __forceinline__ void attn_pass_A2(const int tid, unsigned char* smem, const bf16_t* Q0w, int qpitch, const bf16_t* Kb, int kpitch, const bf16_t* Vb, int vpitch,
;                                              int b, int ntiles, float kmax, f32x16 (&o)[2][2], float (&linv)[2]) {
;     ...
;     for (int qb = 0; qb < 2; ++qb) {
;         const bf16_t* qp = Q0w + (size_t)(32 * qb + r32) * qpitch + 8 * hi; float ssq = 0.f;
; #pragma unroll
;         for (int ds = 0; ds < 4; ++ds) { const bf16x8 qv = *(const bf16x8*)(qp + 16 * ds); *(bf16x8*)(qs + qb * 32 * KP + ds * 32) = qv;
; #pragma unroll
;             for (int j = 0; j < 8; ++j) { const float f = bf2f((unsigned short)qv[j]); ssq += f * f; } }
;         nshift[qb] = -sqrtf(sum_x32(ssq)) * kmax;
; #pragma unroll
;         for (int d0 = 0; d0 < 2; ++d0)
; #pragma unroll
;             for (int r = 0; r < 16; ++r) o[qb][d0][r] = 0.f;
;     }
;     const int krow = tid >> 3, kch = tid & 7;
;     u32x4 kreg, vreg;
;     auto gload = [&](int kt) {
;         const size_t rb = kt < 4 ? (size_t)(NLAT + 256 * b + 64 * kt) : (size_t)(SEQ * b + 64 * (kt - 4));
;         kreg = *(const u32x4*)(Kb + (rb + krow) * kpitch + 8 * kch); vreg = *(const u32x4*)(Vb + (rb + krow) * vpitch + 8 * kch);
;     };
;     auto lwrite = [&](int buf) { unsigned char* Ks = smem + buf * BUF; *(u32x4*)(Ks + krow * KP + 16 * kch) = kreg; *(u32x4*)(Ks + KBYTES + krow * VP + 16 * kch) = vreg; };
;     gload(0); lwrite(0); __syncthreads();
	ds_write_b128 v139, v[16:19] offset:47616
	v_lshlrev_b32_e32 v35, 16, v16
	v_cndmask_b32_e32 v14, v14, v15, vcc
	v_sqrt_f32_e32 v15, v14
	v_and_b32_e32 v16, 0xffff0000, v16
	v_mul_f32_e32 v1, v16, v16
	v_lshlrev_b32_e32 v36, 16, v17
	v_fmac_f32_e32 v1, v35, v35
	v_and_b32_e32 v17, 0xffff0000, v17
	v_fmac_f32_e32 v1, v36, v36
	v_add_u32_e32 v16, -1, v15
	v_fmac_f32_e32 v1, v17, v17
	v_add_u32_e32 v17, 1, v15
	v_fma_f32 v20, -v16, v15, v14
	v_fma_f32 v21, -v17, v15, v14
	v_cmp_ge_f32_e64 s[0:1], 0, v20
	v_lshlrev_b32_e32 v51, 16, v18
	v_fmac_f32_e32 v1, v51, v51
	v_cndmask_b32_e64 v15, v15, v16, s[0:1]
	v_cmp_lt_f32_e64 s[0:1], 0, v21
	v_mov_b32_e32 v32, v0
	v_mov_b32_e32 v33, v0
	v_cndmask_b32_e64 v15, v15, v17, s[0:1]
	v_mul_f32_e32 v16, 0x37800000, v15
	v_cndmask_b32_e32 v15, v15, v16, vcc
	v_cmp_class_f32_e32 vcc, v14, v227
	s_lshl_b32 s0, s10, 8
	s_add_i32 s0, s0, 0x8000
	v_cndmask_b32_e32 v14, v15, v14, vcc
	v_mul_f32_e64 v16, v214, -v14
	v_and_b32_e32 v14, 0xffff0000, v18
	v_fmac_f32_e32 v1, v14, v14
	v_lshlrev_b32_e32 v14, 16, v19
	s_ashr_i32 s1, s0, 31
	v_fmac_f32_e32 v1, v14, v14
	v_lshl_add_u64 v[14:15], s[0:1], 0, v[136:137]
	v_lshlrev_b64 v[14:15], 8, v[14:15]
	v_and_b32_e32 v17, 0xffff0000, v19
	v_lshl_add_u64 v[18:19], s[14:15], 0, v[14:15]
	v_lshl_add_u64 v[18:19], v[18:19], 0, v[192:193]
	v_lshl_add_u64 v[14:15], s[16:17], 0, v[14:15]
	v_lshl_add_u64 v[14:15], v[14:15], 0, v[192:193]
	v_fmac_f32_e32 v1, v17, v17
	s_waitcnt vmcnt(4)
	v_lshlrev_b32_e32 v14, 16, v2
	v_fmac_f32_e32 v1, v14, v14
	v_and_b32_e32 v14, 0xffff0000, v2
	v_fmac_f32_e32 v1, v14, v14
	v_lshlrev_b32_e32 v14, 16, v3
	v_fmac_f32_e32 v1, v14, v14
	v_and_b32_e32 v14, 0xffff0000, v3
	v_fmac_f32_e32 v1, v14, v14
	v_lshlrev_b32_e32 v14, 16, v4
	v_fmac_f32_e32 v1, v14, v14
	v_and_b32_e32 v14, 0xffff0000, v4
	v_fmac_f32_e32 v1, v14, v14
	v_lshlrev_b32_e32 v14, 16, v5
	v_fmac_f32_e32 v1, v14, v14
	v_and_b32_e32 v14, 0xffff0000, v5
	v_fmac_f32_e32 v1, v14, v14
	s_waitcnt vmcnt(3)
	v_lshlrev_b32_e32 v14, 16, v6
	v_fmac_f32_e32 v1, v14, v14
	v_and_b32_e32 v14, 0xffff0000, v6
	v_fmac_f32_e32 v1, v14, v14
	v_lshlrev_b32_e32 v14, 16, v7
	v_fmac_f32_e32 v1, v14, v14
	v_and_b32_e32 v14, 0xffff0000, v7
	v_fmac_f32_e32 v1, v14, v14
	v_lshlrev_b32_e32 v14, 16, v8
	v_fmac_f32_e32 v1, v14, v14
	v_and_b32_e32 v14, 0xffff0000, v8
	v_fmac_f32_e32 v1, v14, v14
	v_lshlrev_b32_e32 v14, 16, v9
	v_fmac_f32_e32 v1, v14, v14
	v_and_b32_e32 v14, 0xffff0000, v9
	v_fmac_f32_e32 v1, v14, v14
	s_waitcnt vmcnt(2)
	v_lshlrev_b32_e32 v14, 16, v10
	v_fmac_f32_e32 v1, v14, v14
	v_and_b32_e32 v14, 0xffff0000, v10
	v_fmac_f32_e32 v1, v14, v14
	v_lshlrev_b32_e32 v14, 16, v11
	v_fmac_f32_e32 v1, v14, v14
	v_and_b32_e32 v14, 0xffff0000, v11
	v_fmac_f32_e32 v1, v14, v14
	v_and_b32_e32 v15, 0xffff0000, v12
	v_lshlrev_b32_e32 v14, 16, v12
	v_pk_mul_f32 v[14:15], v[14:15], v[14:15]
	ds_write_b128 v139, v[2:5] offset:47648
	ds_write_b128 v139, v[6:9] offset:47680
	ds_write_b128 v139, v[10:13] offset:47712
	v_add_f32_e32 v1, v14, v1
	v_add_f32_e32 v1, v15, v1
	v_and_b32_e32 v15, 0xffff0000, v13
	v_lshlrev_b32_e32 v14, 16, v13
	v_pk_mul_f32 v[14:15], v[14:15], v[14:15]
	v_mov_b32_e32 v17, v16
	v_add_f32_e32 v1, v14, v1
	v_add_f32_e32 v1, v15, v1
	v_mov_b32_e32 v14, v1
	s_nop 1
	v_permlane32_swap_b32_e32 v1, v14
	v_add_f32_e32 v1, v1, v14
	v_mul_f32_e32 v14, 0x4f800000, v1
	v_cmp_gt_f32_e32 vcc, s2, v1
	v_mov_b32_e32 v18, v16
	v_mov_b32_e32 v19, v16
	v_cndmask_b32_e32 v1, v1, v14, vcc
	v_sqrt_f32_e32 v14, v1
	v_mov_b32_e32 v20, v16
	v_mov_b32_e32 v21, v16
	v_mov_b32_e32 v22, v16
	v_add_u32_e32 v2, -1, v14
	v_fma_f32 v3, -v2, v14, v1
	v_cmp_ge_f32_e64 s[0:1], 0, v3
	v_add_u32_e32 v3, 1, v14
	v_fma_f32 v4, -v3, v14, v1
	v_cndmask_b32_e64 v2, v14, v2, s[0:1]
	v_cmp_lt_f32_e64 s[0:1], 0, v4
	v_mov_b32_e32 v23, v16
	v_mov_b32_e32 v24, v16
	v_cndmask_b32_e64 v2, v2, v3, s[0:1]
	v_mul_f32_e32 v3, 0x37800000, v2
	v_cndmask_b32_e32 v2, v2, v3, vcc
	v_cmp_class_f32_e32 vcc, v1, v227
	s_movk_i32 s0, 0xc0
	v_mul_lo_u32 v172, v136, s0
	v_cndmask_b32_e32 v1, v2, v1, vcc
	v_add3_u32 v2, 0, v212, v192
	v_mul_f32_e64 v80, v214, -v1
	s_waitcnt vmcnt(1)
	ds_write_b128 v2, v[128:131]
	v_mad_u64_u32 v[2:3], s[0:1], v136, 48, v[2:3]
	s_waitcnt vmcnt(0)
	ds_write_b128 v2, v[132:135] offset:9216
	v_mov_b32_e32 v25, v16
	v_mov_b32_e32 v26, v16
	v_mov_b32_e32 v27, v16
	v_mov_b32_e32 v28, v16
	v_mov_b32_e32 v29, v16
	v_mov_b32_e32 v30, v16
	v_mov_b32_e32 v31, v16
	v_mov_b32_e32 v81, v80
	v_mov_b32_e32 v82, v80
	v_mov_b32_e32 v83, v80
	v_mov_b32_e32 v84, v80
	v_mov_b32_e32 v85, v80
	v_mov_b32_e32 v86, v80
	v_mov_b32_e32 v87, v80
	v_mov_b32_e32 v88, v80
	v_mov_b32_e32 v89, v80
	v_mov_b32_e32 v90, v80
	v_mov_b32_e32 v91, v80
	v_mov_b32_e32 v92, v80
	v_mov_b32_e32 v93, v80
	v_mov_b32_e32 v94, v80
	v_mov_b32_e32 v95, v80
	s_mov_b32 s2, 64
	v_mov_b32_e32 v1, v0
	v_mov_b32_e32 v2, v0
	v_mov_b32_e32 v3, v0
	v_mov_b32_e32 v4, v0
	v_mov_b32_e32 v5, v0
	v_mov_b32_e32 v6, v0
	v_mov_b32_e32 v7, v0
	v_mov_b32_e32 v8, v0
	v_mov_b32_e32 v9, v0
	v_mov_b32_e32 v10, v0
	v_mov_b32_e32 v11, v0
	v_mov_b32_e32 v12, v0
	v_mov_b32_e32 v13, v0
	v_mov_b32_e32 v14, v0
	v_mov_b32_e32 v15, v0
	v_mov_b32_e32 v34, v0
	v_mov_b32_e32 v35, v0
	v_mov_b32_e32 v36, v0
	v_mov_b32_e32 v37, v0
	v_mov_b32_e32 v38, v0
	v_mov_b32_e32 v39, v0
	v_mov_b32_e32 v40, v0
	v_mov_b32_e32 v41, v0
	v_mov_b32_e32 v42, v0
	v_mov_b32_e32 v43, v0
	v_mov_b32_e32 v44, v0
	v_mov_b32_e32 v45, v0
	v_mov_b32_e32 v46, v0
	v_mov_b32_e32 v47, v0
	v_mov_b32_e32 v48, v0
	v_mov_b32_e32 v49, v0
	v_mov_b32_e32 v50, v0
	v_mov_b32_e32 v51, v0
	s_waitcnt lgkmcnt(0)
	s_barrier
; __device__ __forceinline__ void attn_pass_A2(const int tid, unsigned char* smem, const bf16_t* Q0w, int qpitch, const bf16_t* Kb, int kpitch, const bf16_t* Vb, int vpitch,
;                                              int b, int ntiles, float kmax, f32x16 (&o)[2][2], float (&linv)[2]) {
;     ...
;     gload(0); lwrite(0); __syncthreads();
;     const int nhalf = (lane >> 4) & 1, q4 = (lane & 15) >> 2, p4 = lane & 3;
;     for (int kt = 0; kt < ntiles; ++kt) {
;         if (kt + 1 < ntiles) gload(kt + 1);
;         const unsigned char* Ks = smem + (kt & 1) * BUF; const unsigned char* Vs = Ks + KBYTES;
;         const unsigned char* kp = Ks + r32 * KP + hi * 16;
;         const unsigned char* vp = Vs + (4 * hi + q4) * VP + (16 * nhalf + 4 * p4) * 2;
; #pragma unroll
;         for (int kb = 0; kb < 2; ++kb) {
;             bf16x8 pf[2][2];
;             {
;                 f32x16 s0, s1;
; #pragma unroll
;                 for (int r = 0; r < 16; ++r) { s0[r] = nshift[0]; s1[r] = nshift[1]; }
; #pragma unroll
;                 for (int ds = 0; ds < 4; ++ds) {
;                     const bf16x8 kf = *(const bf16x8*)(kp + kb * 32 * KP + ds * 32);
;                     const bf16x8 q0 = *(const bf16x8*)(qs + ds * 32), q1 = *(const bf16x8*)(qs + 32 * KP + ds * 32);
;                     s0 = __builtin_amdgcn_mfma_f32_32x32x16_bf16(kf, q0, s0, 0, 0, 0);
;                     s1 = __builtin_amdgcn_mfma_f32_32x32x16_bf16(kf, q1, s1, 0, 0, 0);
;                 }
;                 float l0 = 0.f, l1 = 0.f;
; #pragma unroll
;                 for (int r = 0; r < 16; ++r) { s0[r] = __builtin_amdgcn_exp2f(s0[r]); l0 += s0[r]; }
; #pragma unroll
;                 for (int r = 0; r < 16; ++r) { s1[r] = __builtin_amdgcn_exp2f(s1[r]); l1 += s1[r]; }
;                 lsum[0] += l0; lsum[1] += l1;
; #pragma unroll
;                 for (int j = 0; j < 2; ++j) {
;                     u32x4 w0, w1;
;                     w0.x = cvt_pk_bf16(s0[8 * j + 0], s0[8 * j + 1]); w0.y = cvt_pk_bf16(s0[8 * j + 2], s0[8 * j + 3]); w0.z = cvt_pk_bf16(s0[8 * j + 4], s0[8 * j + 5]); w0.w = cvt_pk_bf16(s0[8 * j + 6], s0[8 * j + 7]);
;                     w1.x = cvt_pk_bf16(s1[8 * j + 0], s1[8 * j + 1]); w1.y = cvt_pk_bf16(s1[8 * j + 2], s1[8 * j + 3]); w1.z = cvt_pk_bf16(s1[8 * j + 4], s1[8 * j + 5]); w1.w = cvt_pk_bf16(s1[8 * j + 6], s1[8 * j + 7]);
	v_min_f32_e32 v16, v16, v80
	v_mov_b32_e32 v17, v16
	v_mov_b32_e32 v18, v16
	v_mov_b32_e32 v19, v16
	v_mov_b32_e32 v20, v16
	v_mov_b32_e32 v21, v16
	v_mov_b32_e32 v22, v16
	v_mov_b32_e32 v23, v16
	v_mov_b32_e32 v24, v16
	v_mov_b32_e32 v25, v16
	v_mov_b32_e32 v26, v16
	v_mov_b32_e32 v27, v16
	v_mov_b32_e32 v28, v16
	v_mov_b32_e32 v29, v16
	v_mov_b32_e32 v30, v16
	v_mov_b32_e32 v31, v16
	ds_read_b128 v[146:149], v139 offset:43008
	ds_read_b128 v[150:153], v139 offset:43040
	ds_read_b128 v[154:157], v139 offset:43072
	ds_read_b128 v[158:161], v139 offset:43104
	ds_read_b128 v[176:179], v139 offset:47616
	ds_read_b128 v[180:183], v139 offset:47648
	ds_read_b128 v[184:187], v139 offset:47680
	ds_read_b128 v[188:191], v139 offset:47712
	s_mov_b32 s56, 0
	s_movk_i32 s57, 0x5400
	s_mov_b32 s58, 0xa800
	s_mov_b32 s59, 0
	v_add3_u32 v234, s57, v212, v192
	v_add3_u32 v235, s57, v172, v192
	s_waitcnt vmcnt(0)
	ds_write_b128 v234, v[222:225]
	ds_write_b128 v235, v[230:233] offset:9216
	s_waitcnt lgkmcnt(0)
	s_barrier
	s_add_i32 s71, s25, -1
	s_add_i32 s70, s59, 2
	s_min_u32 s70, s70, s71
	s_cmp_lt_u32 s70, 4
	s_cselect_b32 s2, s65, s32
	s_lshl_b32 s3, s70, 6
	s_add_i32 s2, s2, s3
	s_lshl_b32 s2, s2, 8
	s_add_u32 s60, s66, s2
	s_addc_u32 s61, s67, 0
	s_add_u32 s62, s68, s2
	s_addc_u32 s63, s69, 0
	global_load_dwordx4 v[132:135], v236, s[60:61]
	global_load_dwordx4 v[230:233], v236, s[62:63]
	v_add3_u32 v170, s57, v213, v138
	v_add3_u32 v171, s56, v173, v174
	v_add3_u32 v210, s57, v173, v174
	v_add3_u32 v234, s56, v213, v138
	ds_read_b128 v[198:201], v234 offset:0
	ds_read_b128 v[202:205], v234 offset:32
	ds_read_b128 v[206:209], v234 offset:64
	ds_read_b128 v[128:131], v234 offset:96
	s_waitcnt lgkmcnt(3)
	v_mfma_f32_32x32x16_bf16 v[80:95], v[198:201], v[146:149], v[16:31]
	s_waitcnt lgkmcnt(2)
	v_mfma_f32_32x32x16_bf16 v[80:95], v[202:205], v[150:153], v[80:95]
	s_waitcnt lgkmcnt(1)
	v_mfma_f32_32x32x16_bf16 v[80:95], v[206:209], v[154:157], v[80:95]
	s_waitcnt lgkmcnt(0)
	v_mfma_f32_32x32x16_bf16 v[80:95], v[128:131], v[158:161], v[80:95]
	s_nop 7
	s_nop 3
	v_mfma_f32_32x32x16_bf16 v[96:111], v[198:201], v[176:179], v[16:31]
	ds_read_b128 v[198:201], v234 offset:4608
	v_exp_f32_e32 v80, v80
	v_exp_f32_e32 v81, v81
	v_exp_f32_e32 v82, v82
	v_add_f32_e32 v144, v144, v80
	v_exp_f32_e32 v83, v83
	v_add_f32_e32 v144, v144, v81
	v_cvt_pk_bf16_f32 v112, v80, v81
	v_exp_f32_e32 v84, v84
	v_add_f32_e32 v144, v144, v82
	v_exp_f32_e32 v85, v85
	v_add_f32_e32 v144, v144, v83
	v_cvt_pk_bf16_f32 v113, v82, v83
	v_exp_f32_e32 v86, v86
	v_mfma_f32_32x32x16_bf16 v[96:111], v[202:205], v[180:183], v[96:111]
	ds_read_b128 v[202:205], v234 offset:4640
	v_add_f32_e32 v144, v144, v84
	v_exp_f32_e32 v87, v87
	v_add_f32_e32 v144, v144, v85
	v_cvt_pk_bf16_f32 v114, v84, v85
	v_exp_f32_e32 v88, v88
	v_add_f32_e32 v144, v144, v86
	v_exp_f32_e32 v89, v89
	v_add_f32_e32 v144, v144, v87
	v_cvt_pk_bf16_f32 v115, v86, v87
	v_exp_f32_e32 v90, v90
	v_add_f32_e32 v144, v144, v88
	v_exp_f32_e32 v91, v91
	v_add_f32_e32 v144, v144, v89
	v_mfma_f32_32x32x16_bf16 v[96:111], v[206:209], v[184:187], v[96:111]
	ds_read_b128 v[206:209], v234 offset:4672
	v_cvt_pk_bf16_f32 v116, v88, v89
	v_exp_f32_e32 v92, v92
	v_add_f32_e32 v144, v144, v90
	v_exp_f32_e32 v93, v93
	v_add_f32_e32 v144, v144, v91
	v_cvt_pk_bf16_f32 v117, v90, v91
	v_exp_f32_e32 v94, v94
	v_add_f32_e32 v144, v144, v92
	v_exp_f32_e32 v95, v95
	v_add_f32_e32 v144, v144, v93
	v_cvt_pk_bf16_f32 v118, v92, v93
	v_add_f32_e32 v144, v144, v94
	v_add_f32_e32 v144, v144, v95
	v_cvt_pk_bf16_f32 v119, v94, v95
	v_mfma_f32_32x32x16_bf16 v[96:111], v[128:131], v[188:191], v[96:111]
	ds_read_b128 v[128:131], v234 offset:4704
	ds_read_b64_tr_b16 v[162:163], v171 offset:9216
	ds_read_b64_tr_b16 v[164:165], v171 offset:10752
	ds_read_b64_tr_b16 v[166:167], v171 offset:9280
	ds_read_b64_tr_b16 v[168:169], v171 offset:10816
	ds_read_b64_tr_b16 v[214:215], v171 offset:12288
	ds_read_b64_tr_b16 v[216:217], v171 offset:13824
	ds_read_b64_tr_b16 v[218:219], v171 offset:12352
	ds_read_b64_tr_b16 v[220:221], v171 offset:13888
	s_waitcnt lgkmcnt(8)
	s_nop 3
.Laattn_loop:
	v_mfma_f32_32x32x16_bf16 v[80:95], v[198:201], v[146:149], v[16:31]
	v_add3_u32 v234, s58, v212, v192
	v_add3_u32 v235, s58, v172, v192
	v_exp_f32_e32 v96, v96
	v_exp_f32_e32 v97, v97
	v_exp_f32_e32 v98, v98
	v_add_f32_e32 v145, v145, v96
	v_exp_f32_e32 v99, v99
	v_mfma_f32_32x32x16_bf16 v[80:95], v[202:205], v[150:153], v[80:95]
	s_waitcnt vmcnt(0)
	ds_write_b128 v234, v[132:135]
	v_add_f32_e32 v145, v145, v97
	v_cvt_pk_bf16_f32 v120, v96, v97
	v_exp_f32_e32 v100, v100
	v_add_f32_e32 v145, v145, v98
	v_exp_f32_e32 v101, v101
	v_mfma_f32_32x32x16_bf16 v[80:95], v[206:209], v[154:157], v[80:95]
	ds_write_b128 v235, v[230:233] offset:9216
	v_add_f32_e32 v145, v145, v99
	v_cvt_pk_bf16_f32 v121, v98, v99
	v_exp_f32_e32 v102, v102
	v_add_f32_e32 v145, v145, v100
	v_exp_f32_e32 v103, v103
	v_add_f32_e32 v145, v145, v101
	v_mfma_f32_32x32x16_bf16 v[80:95], v[128:131], v[158:161], v[80:95]
	s_add_i32 s71, s25, -1
	s_add_i32 s70, s59, 3
	s_min_u32 s70, s70, s71
	s_cmp_lt_u32 s70, 4
	s_cselect_b32 s2, s65, s32
	s_lshl_b32 s3, s70, 6
	s_add_i32 s2, s2, s3
	s_lshl_b32 s2, s2, 8
	s_add_u32 s60, s66, s2
	s_addc_u32 s61, s67, 0
	s_add_u32 s62, s68, s2
	s_addc_u32 s63, s69, 0
	v_cvt_pk_bf16_f32 v122, v100, v101
	v_exp_f32_e32 v104, v104
	v_add_f32_e32 v145, v145, v102
	v_exp_f32_e32 v105, v105
	v_add_f32_e32 v145, v145, v103
	v_cvt_pk_bf16_f32 v123, v102, v103
	s_waitcnt lgkmcnt(8)
; __device__ __forceinline__ void attn_pass_A2(const int tid, unsigned char* smem, const bf16_t* Q0w, int qpitch, const bf16_t* Kb, int kpitch, const bf16_t* Vb, int vpitch,
;                                              int b, int ntiles, float kmax, f32x16 (&o)[2][2], float (&linv)[2]) {
;     ...
;     for (int kt = 0; kt < ntiles; ++kt) {
;         if (kt + 1 < ntiles) gload(kt + 1);
;         const unsigned char* Ks = smem + (kt & 1) * BUF; const unsigned char* Vs = Ks + KBYTES;
;         const unsigned char* kp = Ks + r32 * KP + hi * 16;
;         const unsigned char* vp = Vs + (4 * hi + q4) * VP + (16 * nhalf + 4 * p4) * 2;
; #pragma unroll
;         for (int kb = 0; kb < 2; ++kb) {
;             bf16x8 pf[2][2];
;             {
;                 f32x16 s0, s1;
; #pragma unroll
;                 for (int r = 0; r < 16; ++r) { s0[r] = nshift[0]; s1[r] = nshift[1]; }
; #pragma unroll
;                 for (int ds = 0; ds < 4; ++ds) {
;                     const bf16x8 kf = *(const bf16x8*)(kp + kb * 32 * KP + ds * 32);
;                     const bf16x8 q0 = *(const bf16x8*)(qs + ds * 32), q1 = *(const bf16x8*)(qs + 32 * KP + ds * 32);
;                     s0 = __builtin_amdgcn_mfma_f32_32x32x16_bf16(kf, q0, s0, 0, 0, 0);
;                     s1 = __builtin_amdgcn_mfma_f32_32x32x16_bf16(kf, q1, s1, 0, 0, 0);
;                 }
;                 float l0 = 0.f, l1 = 0.f;
; #pragma unroll
;                 for (int r = 0; r < 16; ++r) { s0[r] = __builtin_amdgcn_exp2f(s0[r]); l0 += s0[r]; }
; #pragma unroll
;                 for (int r = 0; r < 16; ++r) { s1[r] = __builtin_amdgcn_exp2f(s1[r]); l1 += s1[r]; }
;                 lsum[0] += l0; lsum[1] += l1;
; #pragma unroll
;                 for (int j = 0; j < 2; ++j) {
;                     u32x4 w0, w1;
;                     w0.x = cvt_pk_bf16(s0[8 * j + 0], s0[8 * j + 1]); w0.y = cvt_pk_bf16(s0[8 * j + 2], s0[8 * j + 3]); w0.z = cvt_pk_bf16(s0[8 * j + 4], s0[8 * j + 5]); w0.w = cvt_pk_bf16(s0[8 * j + 6], s0[8 * j + 7]);
;                     w1.x = cvt_pk_bf16(s1[8 * j + 0], s1[8 * j + 1]); w1.y = cvt_pk_bf16(s1[8 * j + 2], s1[8 * j + 3]); w1.z = cvt_pk_bf16(s1[8 * j + 4], s1[8 * j + 5]); w1.w = cvt_pk_bf16(s1[8 * j + 6], s1[8 * j + 7]);
;                     pf[0][j] = __builtin_bit_cast(bf16x8, w0); pf[1][j] = __builtin_bit_cast(bf16x8, w1);
;                 }
;             }
	v_mfma_f32_32x32x16_bf16 v[64:79], v[162:165], v[112:115], v[64:79]
	global_load_dwordx4 v[132:135], v236, s[60:61]
	global_load_dwordx4 v[230:233], v236, s[62:63]
	v_exp_f32_e32 v106, v106
	v_add_f32_e32 v145, v145, v104
	v_exp_f32_e32 v107, v107
	v_add_f32_e32 v145, v145, v105
	v_cvt_pk_bf16_f32 v124, v104, v105
	v_exp_f32_e32 v108, v108
	s_waitcnt lgkmcnt(6)
	v_mfma_f32_32x32x16_bf16 v[48:63], v[166:169], v[112:115], v[48:63]
	v_add_f32_e32 v145, v145, v106
	v_exp_f32_e32 v109, v109
	v_add_f32_e32 v145, v145, v107
	v_cvt_pk_bf16_f32 v125, v106, v107
	v_exp_f32_e32 v110, v110
	s_waitcnt lgkmcnt(4)
	v_mfma_f32_32x32x16_bf16 v[64:79], v[214:217], v[116:119], v[64:79]
	v_add_f32_e32 v145, v145, v108
	v_exp_f32_e32 v111, v111
	v_add_f32_e32 v145, v145, v109
	v_cvt_pk_bf16_f32 v126, v108, v109
	v_add_f32_e32 v145, v145, v110
	v_add_f32_e32 v145, v145, v111
	v_cvt_pk_bf16_f32 v127, v110, v111
	s_waitcnt lgkmcnt(2)
	v_mfma_f32_32x32x16_bf16 v[48:63], v[218:221], v[116:119], v[48:63]
	v_mfma_f32_32x32x16_bf16 v[96:111], v[198:201], v[176:179], v[16:31]
	ds_read_b128 v[198:201], v170 offset:0
	v_exp_f32_e32 v80, v80
	v_exp_f32_e32 v81, v81
	v_exp_f32_e32 v82, v82
	v_add_f32_e32 v144, v144, v80
	v_exp_f32_e32 v83, v83
	v_mfma_f32_32x32x16_bf16 v[96:111], v[202:205], v[180:183], v[96:111]
	ds_read_b128 v[202:205], v170 offset:32
	v_add_f32_e32 v144, v144, v81
	v_cvt_pk_bf16_f32 v112, v80, v81
	v_exp_f32_e32 v84, v84
	v_add_f32_e32 v144, v144, v82
	v_exp_f32_e32 v85, v85
	v_mfma_f32_32x32x16_bf16 v[96:111], v[206:209], v[184:187], v[96:111]
	ds_read_b128 v[206:209], v170 offset:64
	v_add_f32_e32 v144, v144, v83
	v_cvt_pk_bf16_f32 v113, v82, v83
	v_exp_f32_e32 v86, v86
	v_add_f32_e32 v144, v144, v84
	v_exp_f32_e32 v87, v87
	v_add_f32_e32 v144, v144, v85
	v_mfma_f32_32x32x16_bf16 v[96:111], v[128:131], v[188:191], v[96:111]
	ds_read_b128 v[128:131], v170 offset:96
	v_cvt_pk_bf16_f32 v114, v84, v85
	v_exp_f32_e32 v88, v88
	v_add_f32_e32 v144, v144, v86
	v_exp_f32_e32 v89, v89
	v_add_f32_e32 v144, v144, v87
	v_cvt_pk_bf16_f32 v115, v86, v87
	v_mfma_f32_32x32x16_bf16 v[32:47], v[162:165], v[120:123], v[32:47]
	ds_read_b64_tr_b16 v[162:163], v171 offset:15360
	ds_read_b64_tr_b16 v[164:165], v171 offset:16896
	v_exp_f32_e32 v90, v90
	v_add_f32_e32 v144, v144, v88
	v_exp_f32_e32 v91, v91
	v_add_f32_e32 v144, v144, v89
	v_cvt_pk_bf16_f32 v116, v88, v89
	v_exp_f32_e32 v92, v92
	v_mfma_f32_32x32x16_bf16 v[0:15], v[166:169], v[120:123], v[0:15]
	ds_read_b64_tr_b16 v[166:167], v171 offset:15424
	ds_read_b64_tr_b16 v[168:169], v171 offset:16960
	v_add_f32_e32 v144, v144, v90
	v_exp_f32_e32 v93, v93
	v_add_f32_e32 v144, v144, v91
	v_cvt_pk_bf16_f32 v117, v90, v91
	v_exp_f32_e32 v94, v94
	v_mfma_f32_32x32x16_bf16 v[32:47], v[214:217], v[124:127], v[32:47]
	ds_read_b64_tr_b16 v[214:215], v171 offset:18432
	ds_read_b64_tr_b16 v[216:217], v171 offset:19968
	v_add_f32_e32 v144, v144, v92
	v_exp_f32_e32 v95, v95
	v_add_f32_e32 v144, v144, v93
	v_cvt_pk_bf16_f32 v118, v92, v93
	v_add_f32_e32 v144, v144, v94
	v_add_f32_e32 v144, v144, v95
	v_cvt_pk_bf16_f32 v119, v94, v95
	v_mfma_f32_32x32x16_bf16 v[0:15], v[218:221], v[124:127], v[0:15]
	ds_read_b64_tr_b16 v[218:219], v171 offset:18496
	ds_read_b64_tr_b16 v[220:221], v171 offset:20032
	s_waitcnt lgkmcnt(11)
	v_mfma_f32_32x32x16_bf16 v[80:95], v[198:201], v[146:149], v[16:31]
	v_exp_f32_e32 v96, v96
	v_exp_f32_e32 v97, v97
	v_exp_f32_e32 v98, v98
	v_add_f32_e32 v145, v145, v96
	v_exp_f32_e32 v99, v99
	s_waitcnt lgkmcnt(10)
	v_mfma_f32_32x32x16_bf16 v[80:95], v[202:205], v[150:153], v[80:95]
	v_add_f32_e32 v145, v145, v97
	v_cvt_pk_bf16_f32 v120, v96, v97
	v_exp_f32_e32 v100, v100
	v_add_f32_e32 v145, v145, v98
	v_exp_f32_e32 v101, v101
	s_waitcnt lgkmcnt(9)
	v_mfma_f32_32x32x16_bf16 v[80:95], v[206:209], v[154:157], v[80:95]
	v_add_f32_e32 v145, v145, v99
	v_cvt_pk_bf16_f32 v121, v98, v99
	v_exp_f32_e32 v102, v102
	v_add_f32_e32 v145, v145, v100
	v_exp_f32_e32 v103, v103
	v_add_f32_e32 v145, v145, v101
	s_waitcnt lgkmcnt(8)
	v_mfma_f32_32x32x16_bf16 v[80:95], v[128:131], v[158:161], v[80:95]
	v_cvt_pk_bf16_f32 v122, v100, v101
	v_exp_f32_e32 v104, v104
	v_add_f32_e32 v145, v145, v102
	v_exp_f32_e32 v105, v105
	v_add_f32_e32 v145, v145, v103
	v_cvt_pk_bf16_f32 v123, v102, v103
	s_waitcnt lgkmcnt(6)
	v_mfma_f32_32x32x16_bf16 v[64:79], v[162:165], v[112:115], v[64:79]
	v_exp_f32_e32 v106, v106
	v_add_f32_e32 v145, v145, v104
	v_exp_f32_e32 v107, v107
	v_add_f32_e32 v145, v145, v105
	v_cvt_pk_bf16_f32 v124, v104, v105
	v_exp_f32_e32 v108, v108
	s_waitcnt lgkmcnt(4)
	v_mfma_f32_32x32x16_bf16 v[48:63], v[166:169], v[112:115], v[48:63]
	v_add_f32_e32 v145, v145, v106
	v_exp_f32_e32 v109, v109
	v_add_f32_e32 v145, v145, v107
	v_cvt_pk_bf16_f32 v125, v106, v107
	v_exp_f32_e32 v110, v110
	s_waitcnt lgkmcnt(2)
	v_mfma_f32_32x32x16_bf16 v[64:79], v[214:217], v[116:119], v[64:79]
	v_add_f32_e32 v145, v145, v108
	v_exp_f32_e32 v111, v111
	v_add_f32_e32 v145, v145, v109
	v_cvt_pk_bf16_f32 v126, v108, v109
	v_add_f32_e32 v145, v145, v110
	v_add_f32_e32 v145, v145, v111
	v_cvt_pk_bf16_f32 v127, v110, v111
	s_waitcnt lgkmcnt(0)
; __device__ __forceinline__ void attn_pass_A2(const int tid, unsigned char* smem, const bf16_t* Q0w, int qpitch, const bf16_t* Kb, int kpitch, const bf16_t* Vb, int vpitch,
;                                              int b, int ntiles, float kmax, f32x16 (&o)[2][2], float (&linv)[2]) {
;     ...
;     for (int kt = 0; kt < ntiles; ++kt) {
;         if (kt + 1 < ntiles) gload(kt + 1);
;         const unsigned char* Ks = smem + (kt & 1) * BUF; const unsigned char* Vs = Ks + KBYTES;
;         const unsigned char* kp = Ks + r32 * KP + hi * 16;
;         const unsigned char* vp = Vs + (4 * hi + q4) * VP + (16 * nhalf + 4 * p4) * 2;
; #pragma unroll
;         for (int kb = 0; kb < 2; ++kb) {
;             bf16x8 pf[2][2];
;             {
;                 f32x16 s0, s1;
; #pragma unroll
;                 for (int r = 0; r < 16; ++r) { s0[r] = nshift[0]; s1[r] = nshift[1]; }
; #pragma unroll
;                 for (int ds = 0; ds < 4; ++ds) {
;                     const bf16x8 kf = *(const bf16x8*)(kp + kb * 32 * KP + ds * 32);
;                     const bf16x8 q0 = *(const bf16x8*)(qs + ds * 32), q1 = *(const bf16x8*)(qs + 32 * KP + ds * 32);
;                     s0 = __builtin_amdgcn_mfma_f32_32x32x16_bf16(kf, q0, s0, 0, 0, 0);
;                     s1 = __builtin_amdgcn_mfma_f32_32x32x16_bf16(kf, q1, s1, 0, 0, 0);
;                 }
;                 float l0 = 0.f, l1 = 0.f;
; #pragma unroll
;                 for (int r = 0; r < 16; ++r) { s0[r] = __builtin_amdgcn_exp2f(s0[r]); l0 += s0[r]; }
; #pragma unroll
;                 for (int r = 0; r < 16; ++r) { s1[r] = __builtin_amdgcn_exp2f(s1[r]); l1 += s1[r]; }
;                 lsum[0] += l0; lsum[1] += l1;
; #pragma unroll
;                 for (int j = 0; j < 2; ++j) {
;                     u32x4 w0, w1;
;                     w0.x = cvt_pk_bf16(s0[8 * j + 0], s0[8 * j + 1]); w0.y = cvt_pk_bf16(s0[8 * j + 2], s0[8 * j + 3]); w0.z = cvt_pk_bf16(s0[8 * j + 4], s0[8 * j + 5]); w0.w = cvt_pk_bf16(s0[8 * j + 6], s0[8 * j + 7]);
;                     w1.x = cvt_pk_bf16(s1[8 * j + 0], s1[8 * j + 1]); w1.y = cvt_pk_bf16(s1[8 * j + 2], s1[8 * j + 3]); w1.z = cvt_pk_bf16(s1[8 * j + 4], s1[8 * j + 5]); w1.w = cvt_pk_bf16(s1[8 * j + 6], s1[8 * j + 7]);
;                     pf[0][j] = __builtin_bit_cast(bf16x8, w0); pf[1][j] = __builtin_bit_cast(bf16x8, w1);
;                 }
;             }
	v_mfma_f32_32x32x16_bf16 v[48:63], v[218:221], v[116:119], v[48:63]
	v_mfma_f32_32x32x16_bf16 v[96:111], v[198:201], v[176:179], v[16:31]
	ds_read_b128 v[198:201], v170 offset:4608
	v_exp_f32_e32 v80, v80
	v_exp_f32_e32 v81, v81
	v_exp_f32_e32 v82, v82
	v_add_f32_e32 v144, v144, v80
	v_exp_f32_e32 v83, v83
	v_mfma_f32_32x32x16_bf16 v[96:111], v[202:205], v[180:183], v[96:111]
	ds_read_b128 v[202:205], v170 offset:4640
	v_add3_u32 v222, s58, v213, v138
	v_add3_u32 v223, s57, v173, v174
	v_add3_u32 v224, s58, v173, v174
	v_add_f32_e32 v144, v144, v81
	v_cvt_pk_bf16_f32 v112, v80, v81
	v_exp_f32_e32 v84, v84
	v_add_f32_e32 v144, v144, v82
	v_exp_f32_e32 v85, v85
	v_mfma_f32_32x32x16_bf16 v[96:111], v[206:209], v[184:187], v[96:111]
	ds_read_b128 v[206:209], v170 offset:4672
	v_add_f32_e32 v144, v144, v83
	v_cvt_pk_bf16_f32 v113, v82, v83
	v_exp_f32_e32 v86, v86
	v_add_f32_e32 v144, v144, v84
	v_exp_f32_e32 v87, v87
	v_add_f32_e32 v144, v144, v85
	v_mfma_f32_32x32x16_bf16 v[96:111], v[128:131], v[188:191], v[96:111]
	ds_read_b128 v[128:131], v170 offset:4704
	v_cvt_pk_bf16_f32 v114, v84, v85
	v_exp_f32_e32 v88, v88
	v_add_f32_e32 v144, v144, v86
	v_exp_f32_e32 v89, v89
	v_add_f32_e32 v144, v144, v87
	v_cvt_pk_bf16_f32 v115, v86, v87
	v_mfma_f32_32x32x16_bf16 v[32:47], v[162:165], v[120:123], v[32:47]
	ds_read_b64_tr_b16 v[162:163], v210 offset:9216
	ds_read_b64_tr_b16 v[164:165], v210 offset:10752
	v_exp_f32_e32 v90, v90
	v_add_f32_e32 v144, v144, v88
	v_exp_f32_e32 v91, v91
	v_add_f32_e32 v144, v144, v89
	v_cvt_pk_bf16_f32 v116, v88, v89
	v_exp_f32_e32 v92, v92
	v_mfma_f32_32x32x16_bf16 v[0:15], v[166:169], v[120:123], v[0:15]
	ds_read_b64_tr_b16 v[166:167], v210 offset:9280
	ds_read_b64_tr_b16 v[168:169], v210 offset:10816
	s_mov_b32 s2, s56
	s_mov_b32 s56, s57
	s_mov_b32 s57, s58
	s_mov_b32 s58, s2
	s_add_i32 s59, s59, 1
	v_add_f32_e32 v144, v144, v90
	v_exp_f32_e32 v93, v93
	v_add_f32_e32 v144, v144, v91
	v_cvt_pk_bf16_f32 v117, v90, v91
	v_exp_f32_e32 v94, v94
	v_mfma_f32_32x32x16_bf16 v[32:47], v[214:217], v[124:127], v[32:47]
	ds_read_b64_tr_b16 v[214:215], v210 offset:12288
	ds_read_b64_tr_b16 v[216:217], v210 offset:13824
	v_add_f32_e32 v144, v144, v92
	v_exp_f32_e32 v95, v95
	v_add_f32_e32 v144, v144, v93
	v_cvt_pk_bf16_f32 v118, v92, v93
	v_add_f32_e32 v144, v144, v94
	v_add_f32_e32 v144, v144, v95
	v_cvt_pk_bf16_f32 v119, v94, v95
	v_mfma_f32_32x32x16_bf16 v[0:15], v[218:221], v[124:127], v[0:15]
	ds_read_b64_tr_b16 v[218:219], v210 offset:12352
	ds_read_b64_tr_b16 v[220:221], v210 offset:13888
	s_waitcnt lgkmcnt(8)
	s_barrier
	v_mfma_f32_32x32x16_bf16 v[80:95], v[198:201], v[146:149], v[16:31]
	v_add3_u32 v234, s58, v212, v192
	v_add3_u32 v235, s58, v172, v192
	v_exp_f32_e32 v96, v96
	v_exp_f32_e32 v97, v97
	v_exp_f32_e32 v98, v98
	v_add_f32_e32 v145, v145, v96
	v_exp_f32_e32 v99, v99
	v_mfma_f32_32x32x16_bf16 v[80:95], v[202:205], v[150:153], v[80:95]
	s_waitcnt vmcnt(0)
	ds_write_b128 v234, v[132:135]
	v_add_f32_e32 v145, v145, v97
	v_cvt_pk_bf16_f32 v120, v96, v97
	v_exp_f32_e32 v100, v100
	v_add_f32_e32 v145, v145, v98
	v_exp_f32_e32 v101, v101
	v_mfma_f32_32x32x16_bf16 v[80:95], v[206:209], v[154:157], v[80:95]
	ds_write_b128 v235, v[230:233] offset:9216
	v_add_f32_e32 v145, v145, v99
	v_cvt_pk_bf16_f32 v121, v98, v99
	v_exp_f32_e32 v102, v102
	v_add_f32_e32 v145, v145, v100
	v_exp_f32_e32 v103, v103
	v_add_f32_e32 v145, v145, v101
	v_mfma_f32_32x32x16_bf16 v[80:95], v[128:131], v[158:161], v[80:95]
	s_add_i32 s71, s25, -1
	s_add_i32 s70, s59, 3
	s_min_u32 s70, s70, s71
	s_cmp_lt_u32 s70, 4
	s_cselect_b32 s2, s65, s32
	s_lshl_b32 s3, s70, 6
	s_add_i32 s2, s2, s3
	s_lshl_b32 s2, s2, 8
	s_add_u32 s60, s66, s2
	s_addc_u32 s61, s67, 0
	s_add_u32 s62, s68, s2
	s_addc_u32 s63, s69, 0
	v_cvt_pk_bf16_f32 v122, v100, v101
	v_exp_f32_e32 v104, v104
	v_add_f32_e32 v145, v145, v102
	v_exp_f32_e32 v105, v105
	v_add_f32_e32 v145, v145, v103
	v_cvt_pk_bf16_f32 v123, v102, v103
	s_waitcnt lgkmcnt(8)
	v_mfma_f32_32x32x16_bf16 v[64:79], v[162:165], v[112:115], v[64:79]
	global_load_dwordx4 v[132:135], v236, s[60:61]
	global_load_dwordx4 v[230:233], v236, s[62:63]
	v_exp_f32_e32 v106, v106
	v_add_f32_e32 v145, v145, v104
	v_exp_f32_e32 v107, v107
	v_add_f32_e32 v145, v145, v105
	v_cvt_pk_bf16_f32 v124, v104, v105
	v_exp_f32_e32 v108, v108
	s_waitcnt lgkmcnt(6)
	v_mfma_f32_32x32x16_bf16 v[48:63], v[166:169], v[112:115], v[48:63]
	v_add_f32_e32 v145, v145, v106
	v_exp_f32_e32 v109, v109
	v_add_f32_e32 v145, v145, v107
	v_cvt_pk_bf16_f32 v125, v106, v107
	v_exp_f32_e32 v110, v110
	s_waitcnt lgkmcnt(4)
	v_mfma_f32_32x32x16_bf16 v[64:79], v[214:217], v[116:119], v[64:79]
	v_add_f32_e32 v145, v145, v108
	v_exp_f32_e32 v111, v111
	v_add_f32_e32 v145, v145, v109
	v_cvt_pk_bf16_f32 v126, v108, v109
	v_add_f32_e32 v145, v145, v110
	v_add_f32_e32 v145, v145, v111
	v_cvt_pk_bf16_f32 v127, v110, v111
	s_waitcnt lgkmcnt(2)
; __device__ __forceinline__ void attn_pass_A2(const int tid, unsigned char* smem, const bf16_t* Q0w, int qpitch, const bf16_t* Kb, int kpitch, const bf16_t* Vb, int vpitch,
;                                              int b, int ntiles, float kmax, f32x16 (&o)[2][2], float (&linv)[2]) {
;     ...
;     for (int kt = 0; kt < ntiles; ++kt) {
;         if (kt + 1 < ntiles) gload(kt + 1);
;         const unsigned char* Ks = smem + (kt & 1) * BUF; const unsigned char* Vs = Ks + KBYTES;
;         const unsigned char* kp = Ks + r32 * KP + hi * 16;
;         const unsigned char* vp = Vs + (4 * hi + q4) * VP + (16 * nhalf + 4 * p4) * 2;
; #pragma unroll
;         for (int kb = 0; kb < 2; ++kb) {
;             bf16x8 pf[2][2];
;             {
;                 f32x16 s0, s1;
; #pragma unroll
;                 for (int r = 0; r < 16; ++r) { s0[r] = nshift[0]; s1[r] = nshift[1]; }
; #pragma unroll
;                 for (int ds = 0; ds < 4; ++ds) {
;                     const bf16x8 kf = *(const bf16x8*)(kp + kb * 32 * KP + ds * 32);
;                     const bf16x8 q0 = *(const bf16x8*)(qs + ds * 32), q1 = *(const bf16x8*)(qs + 32 * KP + ds * 32);
;                     s0 = __builtin_amdgcn_mfma_f32_32x32x16_bf16(kf, q0, s0, 0, 0, 0);
;                     s1 = __builtin_amdgcn_mfma_f32_32x32x16_bf16(kf, q1, s1, 0, 0, 0);
;                 }
;                 float l0 = 0.f, l1 = 0.f;
; #pragma unroll
;                 for (int r = 0; r < 16; ++r) { s0[r] = __builtin_amdgcn_exp2f(s0[r]); l0 += s0[r]; }
; #pragma unroll
;                 for (int r = 0; r < 16; ++r) { s1[r] = __builtin_amdgcn_exp2f(s1[r]); l1 += s1[r]; }
;                 lsum[0] += l0; lsum[1] += l1;
; #pragma unroll
;                 for (int j = 0; j < 2; ++j) {
;                     u32x4 w0, w1;
;                     w0.x = cvt_pk_bf16(s0[8 * j + 0], s0[8 * j + 1]); w0.y = cvt_pk_bf16(s0[8 * j + 2], s0[8 * j + 3]); w0.z = cvt_pk_bf16(s0[8 * j + 4], s0[8 * j + 5]); w0.w = cvt_pk_bf16(s0[8 * j + 6], s0[8 * j + 7]);
;                     w1.x = cvt_pk_bf16(s1[8 * j + 0], s1[8 * j + 1]); w1.y = cvt_pk_bf16(s1[8 * j + 2], s1[8 * j + 3]); w1.z = cvt_pk_bf16(s1[8 * j + 4], s1[8 * j + 5]); w1.w = cvt_pk_bf16(s1[8 * j + 6], s1[8 * j + 7]);
;                     pf[0][j] = __builtin_bit_cast(bf16x8, w0); pf[1][j] = __builtin_bit_cast(bf16x8, w1);
;                 }
;             }
	v_mfma_f32_32x32x16_bf16 v[48:63], v[218:221], v[116:119], v[48:63]
	v_mfma_f32_32x32x16_bf16 v[96:111], v[198:201], v[176:179], v[16:31]
	ds_read_b128 v[198:201], v222 offset:0
	v_exp_f32_e32 v80, v80
	v_exp_f32_e32 v81, v81
	v_exp_f32_e32 v82, v82
	v_add_f32_e32 v144, v144, v80
	v_exp_f32_e32 v83, v83
	v_mfma_f32_32x32x16_bf16 v[96:111], v[202:205], v[180:183], v[96:111]
	ds_read_b128 v[202:205], v222 offset:32
	v_add_f32_e32 v144, v144, v81
	v_cvt_pk_bf16_f32 v112, v80, v81
	v_exp_f32_e32 v84, v84
	v_add_f32_e32 v144, v144, v82
	v_exp_f32_e32 v85, v85
	v_mfma_f32_32x32x16_bf16 v[96:111], v[206:209], v[184:187], v[96:111]
	ds_read_b128 v[206:209], v222 offset:64
	v_add_f32_e32 v144, v144, v83
	v_cvt_pk_bf16_f32 v113, v82, v83
	v_exp_f32_e32 v86, v86
	v_add_f32_e32 v144, v144, v84
	v_exp_f32_e32 v87, v87
	v_add_f32_e32 v144, v144, v85
	v_mfma_f32_32x32x16_bf16 v[96:111], v[128:131], v[188:191], v[96:111]
	ds_read_b128 v[128:131], v222 offset:96
	v_cvt_pk_bf16_f32 v114, v84, v85
	v_exp_f32_e32 v88, v88
	v_add_f32_e32 v144, v144, v86
	v_exp_f32_e32 v89, v89
	v_add_f32_e32 v144, v144, v87
	v_cvt_pk_bf16_f32 v115, v86, v87
	v_mfma_f32_32x32x16_bf16 v[32:47], v[162:165], v[120:123], v[32:47]
	ds_read_b64_tr_b16 v[162:163], v223 offset:15360
	ds_read_b64_tr_b16 v[164:165], v223 offset:16896
	v_exp_f32_e32 v90, v90
	v_add_f32_e32 v144, v144, v88
	v_exp_f32_e32 v91, v91
	v_add_f32_e32 v144, v144, v89
	v_cvt_pk_bf16_f32 v116, v88, v89
	v_exp_f32_e32 v92, v92
	v_mfma_f32_32x32x16_bf16 v[0:15], v[166:169], v[120:123], v[0:15]
	ds_read_b64_tr_b16 v[166:167], v223 offset:15424
	ds_read_b64_tr_b16 v[168:169], v223 offset:16960
	v_add_f32_e32 v144, v144, v90
	v_exp_f32_e32 v93, v93
	v_add_f32_e32 v144, v144, v91
	v_cvt_pk_bf16_f32 v117, v90, v91
	v_exp_f32_e32 v94, v94
	v_mfma_f32_32x32x16_bf16 v[32:47], v[214:217], v[124:127], v[32:47]
	ds_read_b64_tr_b16 v[214:215], v223 offset:18432
	ds_read_b64_tr_b16 v[216:217], v223 offset:19968
	v_add_f32_e32 v144, v144, v92
	v_exp_f32_e32 v95, v95
	v_add_f32_e32 v144, v144, v93
	v_cvt_pk_bf16_f32 v118, v92, v93
	v_add_f32_e32 v144, v144, v94
	v_add_f32_e32 v144, v144, v95
	v_cvt_pk_bf16_f32 v119, v94, v95
	v_mfma_f32_32x32x16_bf16 v[0:15], v[218:221], v[124:127], v[0:15]
	ds_read_b64_tr_b16 v[218:219], v223 offset:18496
	ds_read_b64_tr_b16 v[220:221], v223 offset:20032
	s_waitcnt lgkmcnt(11)
	v_mfma_f32_32x32x16_bf16 v[80:95], v[198:201], v[146:149], v[16:31]
	v_exp_f32_e32 v96, v96
	v_exp_f32_e32 v97, v97
	v_exp_f32_e32 v98, v98
	v_add_f32_e32 v145, v145, v96
	v_exp_f32_e32 v99, v99
	s_waitcnt lgkmcnt(10)
	v_mfma_f32_32x32x16_bf16 v[80:95], v[202:205], v[150:153], v[80:95]
	v_add_f32_e32 v145, v145, v97
	v_cvt_pk_bf16_f32 v120, v96, v97
	v_exp_f32_e32 v100, v100
	v_add_f32_e32 v145, v145, v98
	v_exp_f32_e32 v101, v101
	s_waitcnt lgkmcnt(9)
	v_mfma_f32_32x32x16_bf16 v[80:95], v[206:209], v[154:157], v[80:95]
	v_add_f32_e32 v145, v145, v99
	v_cvt_pk_bf16_f32 v121, v98, v99
	v_exp_f32_e32 v102, v102
	v_add_f32_e32 v145, v145, v100
	v_exp_f32_e32 v103, v103
	v_add_f32_e32 v145, v145, v101
	s_waitcnt lgkmcnt(8)
	v_mfma_f32_32x32x16_bf16 v[80:95], v[128:131], v[158:161], v[80:95]
	v_cvt_pk_bf16_f32 v122, v100, v101
	v_exp_f32_e32 v104, v104
	v_add_f32_e32 v145, v145, v102
	v_exp_f32_e32 v105, v105
	v_add_f32_e32 v145, v145, v103
	v_cvt_pk_bf16_f32 v123, v102, v103
	s_waitcnt lgkmcnt(6)
	v_mfma_f32_32x32x16_bf16 v[64:79], v[162:165], v[112:115], v[64:79]
	v_exp_f32_e32 v106, v106
	v_add_f32_e32 v145, v145, v104
	v_exp_f32_e32 v107, v107
	v_add_f32_e32 v145, v145, v105
	v_cvt_pk_bf16_f32 v124, v104, v105
	v_exp_f32_e32 v108, v108
	s_waitcnt lgkmcnt(4)
	v_mfma_f32_32x32x16_bf16 v[48:63], v[166:169], v[112:115], v[48:63]
	v_add_f32_e32 v145, v145, v106
	v_exp_f32_e32 v109, v109
	v_add_f32_e32 v145, v145, v107
	v_cvt_pk_bf16_f32 v125, v106, v107
	v_exp_f32_e32 v110, v110
	s_waitcnt lgkmcnt(2)
	v_mfma_f32_32x32x16_bf16 v[64:79], v[214:217], v[116:119], v[64:79]
	v_add_f32_e32 v145, v145, v108
	v_exp_f32_e32 v111, v111
	v_add_f32_e32 v145, v145, v109
	v_cvt_pk_bf16_f32 v126, v108, v109
	v_add_f32_e32 v145, v145, v110
	v_add_f32_e32 v145, v145, v111
	v_cvt_pk_bf16_f32 v127, v110, v111
	s_waitcnt lgkmcnt(0)
	v_mfma_f32_32x32x16_bf16 v[48:63], v[218:221], v[116:119], v[48:63]
	v_mfma_f32_32x32x16_bf16 v[96:111], v[198:201], v[176:179], v[16:31]
	ds_read_b128 v[198:201], v222 offset:4608
	v_exp_f32_e32 v80, v80
	v_exp_f32_e32 v81, v81
	v_exp_f32_e32 v82, v82
	v_add_f32_e32 v144, v144, v80
	v_exp_f32_e32 v83, v83
	v_mfma_f32_32x32x16_bf16 v[96:111], v[202:205], v[180:183], v[96:111]
	ds_read_b128 v[202:205], v222 offset:4640
	v_add3_u32 v170, s58, v213, v138
	v_add3_u32 v171, s57, v173, v174
	v_add3_u32 v210, s58, v173, v174
	v_add_f32_e32 v144, v144, v81
	v_cvt_pk_bf16_f32 v112, v80, v81
	v_exp_f32_e32 v84, v84
	v_add_f32_e32 v144, v144, v82
	v_exp_f32_e32 v85, v85
	v_mfma_f32_32x32x16_bf16 v[96:111], v[206:209], v[184:187], v[96:111]
	ds_read_b128 v[206:209], v222 offset:4672
	v_add_f32_e32 v144, v144, v83
	v_cvt_pk_bf16_f32 v113, v82, v83
	v_exp_f32_e32 v86, v86
	v_add_f32_e32 v144, v144, v84
	v_exp_f32_e32 v87, v87
	v_add_f32_e32 v144, v144, v85
	v_mfma_f32_32x32x16_bf16 v[96:111], v[128:131], v[188:191], v[96:111]
	ds_read_b128 v[128:131], v222 offset:4704
	v_cvt_pk_bf16_f32 v114, v84, v85
	v_exp_f32_e32 v88, v88
	v_add_f32_e32 v144, v144, v86
	v_exp_f32_e32 v89, v89
	v_add_f32_e32 v144, v144, v87
	v_cvt_pk_bf16_f32 v115, v86, v87
	v_mfma_f32_32x32x16_bf16 v[32:47], v[162:165], v[120:123], v[32:47]
	ds_read_b64_tr_b16 v[162:163], v224 offset:9216
	ds_read_b64_tr_b16 v[164:165], v224 offset:10752
	v_exp_f32_e32 v90, v90
	v_add_f32_e32 v144, v144, v88
	v_exp_f32_e32 v91, v91
	v_add_f32_e32 v144, v144, v89
	v_cvt_pk_bf16_f32 v116, v88, v89
	v_exp_f32_e32 v92, v92
	v_mfma_f32_32x32x16_bf16 v[0:15], v[166:169], v[120:123], v[0:15]
	ds_read_b64_tr_b16 v[166:167], v224 offset:9280
	ds_read_b64_tr_b16 v[168:169], v224 offset:10816
	s_mov_b32 s2, s56
	s_mov_b32 s56, s57
	s_mov_b32 s57, s58
	s_mov_b32 s58, s2
	s_add_i32 s59, s59, 1
	v_add_f32_e32 v144, v144, v90
	v_exp_f32_e32 v93, v93
	v_add_f32_e32 v144, v144, v91
	v_cvt_pk_bf16_f32 v117, v90, v91
	v_exp_f32_e32 v94, v94
	v_mfma_f32_32x32x16_bf16 v[32:47], v[214:217], v[124:127], v[32:47]
	ds_read_b64_tr_b16 v[214:215], v224 offset:12288
	ds_read_b64_tr_b16 v[216:217], v224 offset:13824
	v_add_f32_e32 v144, v144, v92
	v_exp_f32_e32 v95, v95
	v_add_f32_e32 v144, v144, v93
	v_cvt_pk_bf16_f32 v118, v92, v93
	v_add_f32_e32 v144, v144, v94
	v_add_f32_e32 v144, v144, v95
	v_cvt_pk_bf16_f32 v119, v94, v95
	v_mfma_f32_32x32x16_bf16 v[0:15], v[218:221], v[124:127], v[0:15]
	ds_read_b64_tr_b16 v[218:219], v224 offset:12352
	ds_read_b64_tr_b16 v[220:221], v224 offset:13888
	s_add_i32 s71, s25, -2
	s_cmp_lt_u32 s59, s71
	s_waitcnt lgkmcnt(8)
	s_barrier
; __device__ __forceinline__ void attn_pass_A2(const int tid, unsigned char* smem, const bf16_t* Q0w, int qpitch, const bf16_t* Kb, int kpitch, const bf16_t* Vb, int vpitch,
;                                              int b, int ntiles, float kmax, f32x16 (&o)[2][2], float (&linv)[2]) {
;     ...
;     for (int kt = 0; kt < ntiles; ++kt) {
;         if (kt + 1 < ntiles) gload(kt + 1);
;         const unsigned char* Ks = smem + (kt & 1) * BUF; const unsigned char* Vs = Ks + KBYTES;
;         const unsigned char* kp = Ks + r32 * KP + hi * 16;
;         const unsigned char* vp = Vs + (4 * hi + q4) * VP + (16 * nhalf + 4 * p4) * 2;
; #pragma unroll
;         for (int kb = 0; kb < 2; ++kb) {
;             bf16x8 pf[2][2];
;             {
;                 f32x16 s0, s1;
; #pragma unroll
;                 for (int r = 0; r < 16; ++r) { s0[r] = nshift[0]; s1[r] = nshift[1]; }
; #pragma unroll
;                 for (int ds = 0; ds < 4; ++ds) {
;                     const bf16x8 kf = *(const bf16x8*)(kp + kb * 32 * KP + ds * 32);
;                     const bf16x8 q0 = *(const bf16x8*)(qs + ds * 32), q1 = *(const bf16x8*)(qs + 32 * KP + ds * 32);
;                     s0 = __builtin_amdgcn_mfma_f32_32x32x16_bf16(kf, q0, s0, 0, 0, 0);
;                     s1 = __builtin_amdgcn_mfma_f32_32x32x16_bf16(kf, q1, s1, 0, 0, 0);
;                 }
;                 float l0 = 0.f, l1 = 0.f;
; #pragma unroll
;                 for (int r = 0; r < 16; ++r) { s0[r] = __builtin_amdgcn_exp2f(s0[r]); l0 += s0[r]; }
; #pragma unroll
;                 for (int r = 0; r < 16; ++r) { s1[r] = __builtin_amdgcn_exp2f(s1[r]); l1 += s1[r]; }
;                 lsum[0] += l0; lsum[1] += l1;
; #pragma unroll
;                 for (int j = 0; j < 2; ++j) {
;                     u32x4 w0, w1;
;                     w0.x = cvt_pk_bf16(s0[8 * j + 0], s0[8 * j + 1]); w0.y = cvt_pk_bf16(s0[8 * j + 2], s0[8 * j + 3]); w0.z = cvt_pk_bf16(s0[8 * j + 4], s0[8 * j + 5]); w0.w = cvt_pk_bf16(s0[8 * j + 6], s0[8 * j + 7]);
;                     w1.x = cvt_pk_bf16(s1[8 * j + 0], s1[8 * j + 1]); w1.y = cvt_pk_bf16(s1[8 * j + 2], s1[8 * j + 3]); w1.z = cvt_pk_bf16(s1[8 * j + 4], s1[8 * j + 5]); w1.w = cvt_pk_bf16(s1[8 * j + 6], s1[8 * j + 7]);
;                     pf[0][j] = __builtin_bit_cast(bf16x8, w0); pf[1][j] = __builtin_bit_cast(bf16x8, w1);
;                 }
;             }
	s_cbranch_scc1 .Laattn_loop
	v_mfma_f32_32x32x16_bf16 v[80:95], v[198:201], v[146:149], v[16:31]
	v_exp_f32_e32 v96, v96
	v_exp_f32_e32 v97, v97
	v_exp_f32_e32 v98, v98
	v_add_f32_e32 v145, v145, v96
	v_exp_f32_e32 v99, v99
	v_mfma_f32_32x32x16_bf16 v[80:95], v[202:205], v[150:153], v[80:95]
	v_add_f32_e32 v145, v145, v97
	v_cvt_pk_bf16_f32 v120, v96, v97
	v_exp_f32_e32 v100, v100
	v_add_f32_e32 v145, v145, v98
	v_exp_f32_e32 v101, v101
	v_mfma_f32_32x32x16_bf16 v[80:95], v[206:209], v[154:157], v[80:95]
	v_add_f32_e32 v145, v145, v99
	v_cvt_pk_bf16_f32 v121, v98, v99
	v_exp_f32_e32 v102, v102
	v_add_f32_e32 v145, v145, v100
	v_exp_f32_e32 v103, v103
	v_add_f32_e32 v145, v145, v101
	v_mfma_f32_32x32x16_bf16 v[80:95], v[128:131], v[158:161], v[80:95]
	v_cvt_pk_bf16_f32 v122, v100, v101
	v_exp_f32_e32 v104, v104
	v_add_f32_e32 v145, v145, v102
	v_exp_f32_e32 v105, v105
	v_add_f32_e32 v145, v145, v103
	v_cvt_pk_bf16_f32 v123, v102, v103
	s_waitcnt lgkmcnt(6)
	v_mfma_f32_32x32x16_bf16 v[64:79], v[162:165], v[112:115], v[64:79]
	v_exp_f32_e32 v106, v106
	v_add_f32_e32 v145, v145, v104
	v_exp_f32_e32 v107, v107
	v_add_f32_e32 v145, v145, v105
	v_cvt_pk_bf16_f32 v124, v104, v105
	v_exp_f32_e32 v108, v108
	s_waitcnt lgkmcnt(4)
	v_mfma_f32_32x32x16_bf16 v[48:63], v[166:169], v[112:115], v[48:63]
	v_add_f32_e32 v145, v145, v106
	v_exp_f32_e32 v109, v109
	v_add_f32_e32 v145, v145, v107
	v_cvt_pk_bf16_f32 v125, v106, v107
	v_exp_f32_e32 v110, v110
	s_waitcnt lgkmcnt(2)
	v_mfma_f32_32x32x16_bf16 v[64:79], v[214:217], v[116:119], v[64:79]
	v_add_f32_e32 v145, v145, v108
	v_exp_f32_e32 v111, v111
	v_add_f32_e32 v145, v145, v109
	v_cvt_pk_bf16_f32 v126, v108, v109
	v_add_f32_e32 v145, v145, v110
	v_add_f32_e32 v145, v145, v111
	v_cvt_pk_bf16_f32 v127, v110, v111
	s_waitcnt lgkmcnt(0)
	v_mfma_f32_32x32x16_bf16 v[48:63], v[218:221], v[116:119], v[48:63]
	v_mfma_f32_32x32x16_bf16 v[96:111], v[198:201], v[176:179], v[16:31]
	ds_read_b128 v[198:201], v170 offset:0
	v_exp_f32_e32 v80, v80
	v_exp_f32_e32 v81, v81
	v_exp_f32_e32 v82, v82
	v_add_f32_e32 v144, v144, v80
	v_exp_f32_e32 v83, v83
	v_mfma_f32_32x32x16_bf16 v[96:111], v[202:205], v[180:183], v[96:111]
	ds_read_b128 v[202:205], v170 offset:32
	v_add_f32_e32 v144, v144, v81
	v_cvt_pk_bf16_f32 v112, v80, v81
	v_exp_f32_e32 v84, v84
	v_add_f32_e32 v144, v144, v82
	v_exp_f32_e32 v85, v85
	v_mfma_f32_32x32x16_bf16 v[96:111], v[206:209], v[184:187], v[96:111]
	ds_read_b128 v[206:209], v170 offset:64
	v_add_f32_e32 v144, v144, v83
	v_cvt_pk_bf16_f32 v113, v82, v83
	v_exp_f32_e32 v86, v86
	v_add_f32_e32 v144, v144, v84
	v_exp_f32_e32 v87, v87
	v_add_f32_e32 v144, v144, v85
	v_mfma_f32_32x32x16_bf16 v[96:111], v[128:131], v[188:191], v[96:111]
	ds_read_b128 v[128:131], v170 offset:96
	v_cvt_pk_bf16_f32 v114, v84, v85
	v_exp_f32_e32 v88, v88
	v_add_f32_e32 v144, v144, v86
	v_exp_f32_e32 v89, v89
	v_add_f32_e32 v144, v144, v87
	v_cvt_pk_bf16_f32 v115, v86, v87
	v_mfma_f32_32x32x16_bf16 v[32:47], v[162:165], v[120:123], v[32:47]
	ds_read_b64_tr_b16 v[162:163], v171 offset:15360
	ds_read_b64_tr_b16 v[164:165], v171 offset:16896
	v_exp_f32_e32 v90, v90
	v_add_f32_e32 v144, v144, v88
	v_exp_f32_e32 v91, v91
	v_add_f32_e32 v144, v144, v89
	v_cvt_pk_bf16_f32 v116, v88, v89
	v_exp_f32_e32 v92, v92
	v_mfma_f32_32x32x16_bf16 v[0:15], v[166:169], v[120:123], v[0:15]
	ds_read_b64_tr_b16 v[166:167], v171 offset:15424
	ds_read_b64_tr_b16 v[168:169], v171 offset:16960
	v_add_f32_e32 v144, v144, v90
	v_exp_f32_e32 v93, v93
	v_add_f32_e32 v144, v144, v91
	v_cvt_pk_bf16_f32 v117, v90, v91
	v_exp_f32_e32 v94, v94
	v_mfma_f32_32x32x16_bf16 v[32:47], v[214:217], v[124:127], v[32:47]
	ds_read_b64_tr_b16 v[214:215], v171 offset:18432
	ds_read_b64_tr_b16 v[216:217], v171 offset:19968
	v_add_f32_e32 v144, v144, v92
	v_exp_f32_e32 v95, v95
	v_add_f32_e32 v144, v144, v93
	v_cvt_pk_bf16_f32 v118, v92, v93
	v_add_f32_e32 v144, v144, v94
	v_add_f32_e32 v144, v144, v95
	v_cvt_pk_bf16_f32 v119, v94, v95
	v_mfma_f32_32x32x16_bf16 v[0:15], v[218:221], v[124:127], v[0:15]
	ds_read_b64_tr_b16 v[218:219], v171 offset:18496
	ds_read_b64_tr_b16 v[220:221], v171 offset:20032
	s_waitcnt lgkmcnt(11)
	v_mfma_f32_32x32x16_bf16 v[80:95], v[198:201], v[146:149], v[16:31]
	v_exp_f32_e32 v96, v96
	v_exp_f32_e32 v97, v97
	v_exp_f32_e32 v98, v98
	v_add_f32_e32 v145, v145, v96
	v_exp_f32_e32 v99, v99
	s_waitcnt lgkmcnt(10)
	v_mfma_f32_32x32x16_bf16 v[80:95], v[202:205], v[150:153], v[80:95]
	v_add_f32_e32 v145, v145, v97
	v_cvt_pk_bf16_f32 v120, v96, v97
	v_exp_f32_e32 v100, v100
	v_add_f32_e32 v145, v145, v98
	v_exp_f32_e32 v101, v101
	s_waitcnt lgkmcnt(9)
	v_mfma_f32_32x32x16_bf16 v[80:95], v[206:209], v[154:157], v[80:95]
	v_add_f32_e32 v145, v145, v99
	v_cvt_pk_bf16_f32 v121, v98, v99
	v_exp_f32_e32 v102, v102
	v_add_f32_e32 v145, v145, v100
	v_exp_f32_e32 v103, v103
	v_add_f32_e32 v145, v145, v101
	s_waitcnt lgkmcnt(8)
	v_mfma_f32_32x32x16_bf16 v[80:95], v[128:131], v[158:161], v[80:95]
	v_cvt_pk_bf16_f32 v122, v100, v101
	v_exp_f32_e32 v104, v104
	v_add_f32_e32 v145, v145, v102
	v_exp_f32_e32 v105, v105
	v_add_f32_e32 v145, v145, v103
	v_cvt_pk_bf16_f32 v123, v102, v103
	s_waitcnt lgkmcnt(6)
	v_mfma_f32_32x32x16_bf16 v[64:79], v[162:165], v[112:115], v[64:79]
	v_exp_f32_e32 v106, v106
	v_add_f32_e32 v145, v145, v104
	v_exp_f32_e32 v107, v107
	v_add_f32_e32 v145, v145, v105
	v_cvt_pk_bf16_f32 v124, v104, v105
	v_exp_f32_e32 v108, v108
	s_waitcnt lgkmcnt(4)
	v_mfma_f32_32x32x16_bf16 v[48:63], v[166:169], v[112:115], v[48:63]
	v_add_f32_e32 v145, v145, v106
	v_exp_f32_e32 v109, v109
	v_add_f32_e32 v145, v145, v107
	v_cvt_pk_bf16_f32 v125, v106, v107
	v_exp_f32_e32 v110, v110
	s_waitcnt lgkmcnt(2)
; __device__ __forceinline__ void attn_pass_A2(const int tid, unsigned char* smem, const bf16_t* Q0w, int qpitch, const bf16_t* Kb, int kpitch, const bf16_t* Vb, int vpitch,
;                                              int b, int ntiles, float kmax, f32x16 (&o)[2][2], float (&linv)[2]) {
;     ...
;     for (int kt = 0; kt < ntiles; ++kt) {
;         if (kt + 1 < ntiles) gload(kt + 1);
;         const unsigned char* Ks = smem + (kt & 1) * BUF; const unsigned char* Vs = Ks + KBYTES;
;         const unsigned char* kp = Ks + r32 * KP + hi * 16;
;         const unsigned char* vp = Vs + (4 * hi + q4) * VP + (16 * nhalf + 4 * p4) * 2;
; #pragma unroll
;         for (int kb = 0; kb < 2; ++kb) {
;             bf16x8 pf[2][2];
;             {
;                 f32x16 s0, s1;
; #pragma unroll
;                 for (int r = 0; r < 16; ++r) { s0[r] = nshift[0]; s1[r] = nshift[1]; }
; #pragma unroll
;                 for (int ds = 0; ds < 4; ++ds) {
;                     const bf16x8 kf = *(const bf16x8*)(kp + kb * 32 * KP + ds * 32);
;                     const bf16x8 q0 = *(const bf16x8*)(qs + ds * 32), q1 = *(const bf16x8*)(qs + 32 * KP + ds * 32);
;                     s0 = __builtin_amdgcn_mfma_f32_32x32x16_bf16(kf, q0, s0, 0, 0, 0);
;                     s1 = __builtin_amdgcn_mfma_f32_32x32x16_bf16(kf, q1, s1, 0, 0, 0);
;                 }
;                 float l0 = 0.f, l1 = 0.f;
; #pragma unroll
;                 for (int r = 0; r < 16; ++r) { s0[r] = __builtin_amdgcn_exp2f(s0[r]); l0 += s0[r]; }
; #pragma unroll
;                 for (int r = 0; r < 16; ++r) { s1[r] = __builtin_amdgcn_exp2f(s1[r]); l1 += s1[r]; }
;                 lsum[0] += l0; lsum[1] += l1;
; #pragma unroll
;                 for (int j = 0; j < 2; ++j) {
;                     u32x4 w0, w1;
;                     w0.x = cvt_pk_bf16(s0[8 * j + 0], s0[8 * j + 1]); w0.y = cvt_pk_bf16(s0[8 * j + 2], s0[8 * j + 3]); w0.z = cvt_pk_bf16(s0[8 * j + 4], s0[8 * j + 5]); w0.w = cvt_pk_bf16(s0[8 * j + 6], s0[8 * j + 7]);
;                     w1.x = cvt_pk_bf16(s1[8 * j + 0], s1[8 * j + 1]); w1.y = cvt_pk_bf16(s1[8 * j + 2], s1[8 * j + 3]); w1.z = cvt_pk_bf16(s1[8 * j + 4], s1[8 * j + 5]); w1.w = cvt_pk_bf16(s1[8 * j + 6], s1[8 * j + 7]);
;                     pf[0][j] = __builtin_bit_cast(bf16x8, w0); pf[1][j] = __builtin_bit_cast(bf16x8, w1);
;                 }
;             }
	v_mfma_f32_32x32x16_bf16 v[64:79], v[214:217], v[116:119], v[64:79]
	v_add_f32_e32 v145, v145, v108
	v_exp_f32_e32 v111, v111
	v_add_f32_e32 v145, v145, v109
	v_cvt_pk_bf16_f32 v126, v108, v109
	v_add_f32_e32 v145, v145, v110
	v_add_f32_e32 v145, v145, v111
	v_cvt_pk_bf16_f32 v127, v110, v111
	s_waitcnt lgkmcnt(0)
	v_mfma_f32_32x32x16_bf16 v[48:63], v[218:221], v[116:119], v[48:63]
	v_mfma_f32_32x32x16_bf16 v[96:111], v[198:201], v[176:179], v[16:31]
	ds_read_b128 v[198:201], v170 offset:4608
	v_exp_f32_e32 v80, v80
	v_exp_f32_e32 v81, v81
	v_exp_f32_e32 v82, v82
	v_add_f32_e32 v144, v144, v80
	v_exp_f32_e32 v83, v83
	v_mfma_f32_32x32x16_bf16 v[96:111], v[202:205], v[180:183], v[96:111]
	ds_read_b128 v[202:205], v170 offset:4640
	v_add3_u32 v222, s58, v213, v138
	v_add3_u32 v223, s57, v173, v174
	v_add3_u32 v224, s58, v173, v174
	v_add_f32_e32 v144, v144, v81
	v_cvt_pk_bf16_f32 v112, v80, v81
	v_exp_f32_e32 v84, v84
	v_add_f32_e32 v144, v144, v82
	v_exp_f32_e32 v85, v85
	v_mfma_f32_32x32x16_bf16 v[96:111], v[206:209], v[184:187], v[96:111]
	ds_read_b128 v[206:209], v170 offset:4672
	v_add_f32_e32 v144, v144, v83
	v_cvt_pk_bf16_f32 v113, v82, v83
	v_exp_f32_e32 v86, v86
	v_add_f32_e32 v144, v144, v84
	v_exp_f32_e32 v87, v87
	v_add_f32_e32 v144, v144, v85
	v_mfma_f32_32x32x16_bf16 v[96:111], v[128:131], v[188:191], v[96:111]
	ds_read_b128 v[128:131], v170 offset:4704
	v_cvt_pk_bf16_f32 v114, v84, v85
	v_exp_f32_e32 v88, v88
	v_add_f32_e32 v144, v144, v86
	v_exp_f32_e32 v89, v89
	v_add_f32_e32 v144, v144, v87
	v_cvt_pk_bf16_f32 v115, v86, v87
	v_mfma_f32_32x32x16_bf16 v[32:47], v[162:165], v[120:123], v[32:47]
	ds_read_b64_tr_b16 v[162:163], v210 offset:9216
	ds_read_b64_tr_b16 v[164:165], v210 offset:10752
	v_exp_f32_e32 v90, v90
	v_add_f32_e32 v144, v144, v88
	v_exp_f32_e32 v91, v91
	v_add_f32_e32 v144, v144, v89
	v_cvt_pk_bf16_f32 v116, v88, v89
	v_exp_f32_e32 v92, v92
	v_mfma_f32_32x32x16_bf16 v[0:15], v[166:169], v[120:123], v[0:15]
	ds_read_b64_tr_b16 v[166:167], v210 offset:9280
	ds_read_b64_tr_b16 v[168:169], v210 offset:10816
	s_mov_b32 s2, s56
	s_mov_b32 s56, s57
	s_mov_b32 s57, s58
	s_mov_b32 s58, s2
	s_add_i32 s59, s59, 1
	v_add_f32_e32 v144, v144, v90
	v_exp_f32_e32 v93, v93
	v_add_f32_e32 v144, v144, v91
	v_cvt_pk_bf16_f32 v117, v90, v91
	v_exp_f32_e32 v94, v94
	v_mfma_f32_32x32x16_bf16 v[32:47], v[214:217], v[124:127], v[32:47]
	ds_read_b64_tr_b16 v[214:215], v210 offset:12288
	ds_read_b64_tr_b16 v[216:217], v210 offset:13824
	v_add_f32_e32 v144, v144, v92
	v_exp_f32_e32 v95, v95
	v_add_f32_e32 v144, v144, v93
	v_cvt_pk_bf16_f32 v118, v92, v93
	v_add_f32_e32 v144, v144, v94
	v_add_f32_e32 v144, v144, v95
	v_cvt_pk_bf16_f32 v119, v94, v95
	v_mfma_f32_32x32x16_bf16 v[0:15], v[218:221], v[124:127], v[0:15]
	ds_read_b64_tr_b16 v[218:219], v210 offset:12352
	ds_read_b64_tr_b16 v[220:221], v210 offset:13888
	s_waitcnt lgkmcnt(8)
	s_barrier
; __device__ __forceinline__ void attn_pass_A2(const int tid, unsigned char* smem, const bf16_t* Q0w, int qpitch, const bf16_t* Kb, int kpitch, const bf16_t* Vb, int vpitch,
;                                              int b, int ntiles, float kmax, f32x16 (&o)[2][2], float (&linv)[2]) {
;     ...
;     for (int kt = 0; kt < ntiles; ++kt) {
;         if (kt + 1 < ntiles) gload(kt + 1);
;         const unsigned char* Ks = smem + (kt & 1) * BUF; const unsigned char* Vs = Ks + KBYTES;
;         const unsigned char* kp = Ks + r32 * KP + hi * 16;
;         const unsigned char* vp = Vs + (4 * hi + q4) * VP + (16 * nhalf + 4 * p4) * 2;
; #pragma unroll
;         for (int kb = 0; kb < 2; ++kb) {
;             bf16x8 pf[2][2];
;             {
;                 f32x16 s0, s1;
; #pragma unroll
;                 for (int r = 0; r < 16; ++r) { s0[r] = nshift[0]; s1[r] = nshift[1]; }
; #pragma unroll
;                 for (int ds = 0; ds < 4; ++ds) {
;                     const bf16x8 kf = *(const bf16x8*)(kp + kb * 32 * KP + ds * 32);
;                     const bf16x8 q0 = *(const bf16x8*)(qs + ds * 32), q1 = *(const bf16x8*)(qs + 32 * KP + ds * 32);
;                     s0 = __builtin_amdgcn_mfma_f32_32x32x16_bf16(kf, q0, s0, 0, 0, 0);
;                     s1 = __builtin_amdgcn_mfma_f32_32x32x16_bf16(kf, q1, s1, 0, 0, 0);
;                 }
;                 float l0 = 0.f, l1 = 0.f;
; #pragma unroll
;                 for (int r = 0; r < 16; ++r) { s0[r] = __builtin_amdgcn_exp2f(s0[r]); l0 += s0[r]; }
; #pragma unroll
;                 for (int r = 0; r < 16; ++r) { s1[r] = __builtin_amdgcn_exp2f(s1[r]); l1 += s1[r]; }
;                 lsum[0] += l0; lsum[1] += l1;
; #pragma unroll
;                 for (int j = 0; j < 2; ++j) {
;                     u32x4 w0, w1;
;                     w0.x = cvt_pk_bf16(s0[8 * j + 0], s0[8 * j + 1]); w0.y = cvt_pk_bf16(s0[8 * j + 2], s0[8 * j + 3]); w0.z = cvt_pk_bf16(s0[8 * j + 4], s0[8 * j + 5]); w0.w = cvt_pk_bf16(s0[8 * j + 6], s0[8 * j + 7]);
;                     w1.x = cvt_pk_bf16(s1[8 * j + 0], s1[8 * j + 1]); w1.y = cvt_pk_bf16(s1[8 * j + 2], s1[8 * j + 3]); w1.z = cvt_pk_bf16(s1[8 * j + 4], s1[8 * j + 5]); w1.w = cvt_pk_bf16(s1[8 * j + 6], s1[8 * j + 7]);
;                     pf[0][j] = __builtin_bit_cast(bf16x8, w0); pf[1][j] = __builtin_bit_cast(bf16x8, w1);
;                 }
;             }
	v_mfma_f32_32x32x16_bf16 v[80:95], v[198:201], v[146:149], v[16:31]
	v_exp_f32_e32 v96, v96
	v_exp_f32_e32 v97, v97
	v_exp_f32_e32 v98, v98
	v_add_f32_e32 v145, v145, v96
	v_exp_f32_e32 v99, v99
	v_mfma_f32_32x32x16_bf16 v[80:95], v[202:205], v[150:153], v[80:95]
	v_add_f32_e32 v145, v145, v97
	v_cvt_pk_bf16_f32 v120, v96, v97
	v_exp_f32_e32 v100, v100
	v_add_f32_e32 v145, v145, v98
	v_exp_f32_e32 v101, v101
	v_mfma_f32_32x32x16_bf16 v[80:95], v[206:209], v[154:157], v[80:95]
	v_add_f32_e32 v145, v145, v99
	v_cvt_pk_bf16_f32 v121, v98, v99
	v_exp_f32_e32 v102, v102
	v_add_f32_e32 v145, v145, v100
	v_exp_f32_e32 v103, v103
	v_add_f32_e32 v145, v145, v101
	v_mfma_f32_32x32x16_bf16 v[80:95], v[128:131], v[158:161], v[80:95]
	v_cvt_pk_bf16_f32 v122, v100, v101
	v_exp_f32_e32 v104, v104
	v_add_f32_e32 v145, v145, v102
	v_exp_f32_e32 v105, v105
	v_add_f32_e32 v145, v145, v103
	v_cvt_pk_bf16_f32 v123, v102, v103
	s_waitcnt lgkmcnt(6)
	v_mfma_f32_32x32x16_bf16 v[64:79], v[162:165], v[112:115], v[64:79]
	v_exp_f32_e32 v106, v106
	v_add_f32_e32 v145, v145, v104
	v_exp_f32_e32 v107, v107
	v_add_f32_e32 v145, v145, v105
	v_cvt_pk_bf16_f32 v124, v104, v105
	v_exp_f32_e32 v108, v108
	s_waitcnt lgkmcnt(4)
	v_mfma_f32_32x32x16_bf16 v[48:63], v[166:169], v[112:115], v[48:63]
	v_add_f32_e32 v145, v145, v106
	v_exp_f32_e32 v109, v109
	v_add_f32_e32 v145, v145, v107
	v_cvt_pk_bf16_f32 v125, v106, v107
	v_exp_f32_e32 v110, v110
	s_waitcnt lgkmcnt(2)
	v_mfma_f32_32x32x16_bf16 v[64:79], v[214:217], v[116:119], v[64:79]
	v_add_f32_e32 v145, v145, v108
	v_exp_f32_e32 v111, v111
	v_add_f32_e32 v145, v145, v109
	v_cvt_pk_bf16_f32 v126, v108, v109
	v_add_f32_e32 v145, v145, v110
	v_add_f32_e32 v145, v145, v111
	v_cvt_pk_bf16_f32 v127, v110, v111
	s_waitcnt lgkmcnt(0)
	v_mfma_f32_32x32x16_bf16 v[48:63], v[218:221], v[116:119], v[48:63]
	v_mfma_f32_32x32x16_bf16 v[96:111], v[198:201], v[176:179], v[16:31]
	v_exp_f32_e32 v80, v80
	v_exp_f32_e32 v81, v81
	v_exp_f32_e32 v82, v82
	v_add_f32_e32 v144, v144, v80
	v_exp_f32_e32 v83, v83
	v_mfma_f32_32x32x16_bf16 v[96:111], v[202:205], v[180:183], v[96:111]
	v_add_f32_e32 v144, v144, v81
	v_cvt_pk_bf16_f32 v112, v80, v81
	v_exp_f32_e32 v84, v84
	v_add_f32_e32 v144, v144, v82
	v_exp_f32_e32 v85, v85
	v_mfma_f32_32x32x16_bf16 v[96:111], v[206:209], v[184:187], v[96:111]
	v_add_f32_e32 v144, v144, v83
	v_cvt_pk_bf16_f32 v113, v82, v83
	v_exp_f32_e32 v86, v86
	v_add_f32_e32 v144, v144, v84
	v_exp_f32_e32 v87, v87
	v_add_f32_e32 v144, v144, v85
	v_mfma_f32_32x32x16_bf16 v[96:111], v[128:131], v[188:191], v[96:111]
	v_cvt_pk_bf16_f32 v114, v84, v85
	v_exp_f32_e32 v88, v88
	v_add_f32_e32 v144, v144, v86
	v_exp_f32_e32 v89, v89
	v_add_f32_e32 v144, v144, v87
	v_cvt_pk_bf16_f32 v115, v86, v87
	v_mfma_f32_32x32x16_bf16 v[32:47], v[162:165], v[120:123], v[32:47]
	ds_read_b64_tr_b16 v[162:163], v223 offset:15360
	ds_read_b64_tr_b16 v[164:165], v223 offset:16896
	v_exp_f32_e32 v90, v90
	v_add_f32_e32 v144, v144, v88
	v_exp_f32_e32 v91, v91
	v_add_f32_e32 v144, v144, v89
	v_cvt_pk_bf16_f32 v116, v88, v89
	v_exp_f32_e32 v92, v92
	v_mfma_f32_32x32x16_bf16 v[0:15], v[166:169], v[120:123], v[0:15]
	ds_read_b64_tr_b16 v[166:167], v223 offset:15424
	ds_read_b64_tr_b16 v[168:169], v223 offset:16960
	v_add_f32_e32 v144, v144, v90
	v_exp_f32_e32 v93, v93
	v_add_f32_e32 v144, v144, v91
	v_cvt_pk_bf16_f32 v117, v90, v91
	v_exp_f32_e32 v94, v94
	v_mfma_f32_32x32x16_bf16 v[32:47], v[214:217], v[124:127], v[32:47]
	ds_read_b64_tr_b16 v[214:215], v223 offset:18432
	ds_read_b64_tr_b16 v[216:217], v223 offset:19968
	v_add_f32_e32 v144, v144, v92
	v_exp_f32_e32 v95, v95
	v_add_f32_e32 v144, v144, v93
	v_cvt_pk_bf16_f32 v118, v92, v93
	v_add_f32_e32 v144, v144, v94
	v_add_f32_e32 v144, v144, v95
	v_cvt_pk_bf16_f32 v119, v94, v95
	v_mfma_f32_32x32x16_bf16 v[0:15], v[218:221], v[124:127], v[0:15]
	ds_read_b64_tr_b16 v[218:219], v223 offset:18496
	ds_read_b64_tr_b16 v[220:221], v223 offset:20032
	s_waitcnt lgkmcnt(6)
	v_mfma_f32_32x32x16_bf16 v[64:79], v[162:165], v[112:115], v[64:79]
	v_exp_f32_e32 v96, v96
	v_exp_f32_e32 v97, v97
	v_exp_f32_e32 v98, v98
	v_add_f32_e32 v145, v145, v96
	v_exp_f32_e32 v99, v99
	v_add_f32_e32 v145, v145, v97
	v_cvt_pk_bf16_f32 v120, v96, v97
	v_exp_f32_e32 v100, v100
	v_add_f32_e32 v145, v145, v98
	v_exp_f32_e32 v101, v101
	v_add_f32_e32 v145, v145, v99
	v_cvt_pk_bf16_f32 v121, v98, v99
	v_exp_f32_e32 v102, v102
	s_waitcnt lgkmcnt(4)
	v_mfma_f32_32x32x16_bf16 v[48:63], v[166:169], v[112:115], v[48:63]
	v_add_f32_e32 v145, v145, v100
	v_exp_f32_e32 v103, v103
	v_add_f32_e32 v145, v145, v101
	v_cvt_pk_bf16_f32 v122, v100, v101
	v_exp_f32_e32 v104, v104
	v_add_f32_e32 v145, v145, v102
	v_exp_f32_e32 v105, v105
	v_add_f32_e32 v145, v145, v103
	v_cvt_pk_bf16_f32 v123, v102, v103
	v_exp_f32_e32 v106, v106
	v_add_f32_e32 v145, v145, v104
	v_exp_f32_e32 v107, v107
	v_add_f32_e32 v145, v145, v105
	s_waitcnt lgkmcnt(2)
	v_mfma_f32_32x32x16_bf16 v[64:79], v[214:217], v[116:119], v[64:79]
	v_cvt_pk_bf16_f32 v124, v104, v105
	v_exp_f32_e32 v108, v108
	v_add_f32_e32 v145, v145, v106
	v_exp_f32_e32 v109, v109
	v_add_f32_e32 v145, v145, v107
	v_cvt_pk_bf16_f32 v125, v106, v107
	v_exp_f32_e32 v110, v110
	v_add_f32_e32 v145, v145, v108
	v_exp_f32_e32 v111, v111
	v_add_f32_e32 v145, v145, v109
	v_cvt_pk_bf16_f32 v126, v108, v109
	v_add_f32_e32 v145, v145, v110
	v_add_f32_e32 v145, v145, v111
	v_cvt_pk_bf16_f32 v127, v110, v111
	s_waitcnt lgkmcnt(0)
	v_mfma_f32_32x32x16_bf16 v[48:63], v[218:221], v[116:119], v[48:63]
	v_mfma_f32_32x32x16_bf16 v[32:47], v[162:165], v[120:123], v[32:47]
	v_mfma_f32_32x32x16_bf16 v[0:15], v[166:169], v[120:123], v[0:15]
	v_mfma_f32_32x32x16_bf16 v[32:47], v[214:217], v[124:127], v[32:47]
	v_mfma_f32_32x32x16_bf16 v[0:15], v[218:221], v[124:127], v[0:15]
	s_waitcnt lgkmcnt(0)
	s_barrier
	s_waitcnt vmcnt(0)
